# IN0 epilogue (P1): per-pass ssin global loads served from an LDS copy staged once per tile
# speedup vs baseline: 1.0146x; 1.0051x over previous
.LBB0_73:
	s_bfe_u32 s4, s44, 0x80003
	s_mul_i32 s4, s4, 19
	s_lshr_b32 s4, s4, 9
	s_lshr_b32 s51, s44, 3
	s_mul_i32 s4, s4, 27
	s_sub_i32 s4, s51, s4
	s_and_b32 s76, s4, 0xff
	s_bfe_u32 s4, s44, 0xd0003
	s_mulk_i32 s4, 0x12f7
	s_lshr_b32 s4, s4, 11
	s_lshl_b32 s5, s44, 3
	s_and_b32 s4, s4, 0x7fc0
	s_and_b32 s5, s5, 56
	s_or_b32 s4, s5, s4
	s_or_b32 s4, s4, s3
	s_lshl_b32 s26, s4, 7
	s_lshl_b64 s[4:5], s[26:27], 11
	v_lshl_add_u64 v[160:161], v[144:145], 0, s[4:5]
	v_add_co_u32_e32 v162, vcc, s47, v160
	s_lshl_b32 s4, s76, 18
	s_nop 0
	v_addc_co_u32_e32 v163, vcc, 0, v161, vcc
	s_mov_b32 s5, s27
	v_add_co_u32_e32 v164, vcc, s87, v160
	v_lshl_add_u64 v[158:159], v[146:147], 0, s[4:5]
	s_nop 0
	v_addc_co_u32_e32 v165, vcc, 0, v161, vcc
	v_add_co_u32_e32 v166, vcc, s47, v158
	global_load_dwordx4 v[2:5], v[160:161], off
	global_load_dwordx4 v[6:9], v[162:163], off
	v_addc_co_u32_e32 v167, vcc, 0, v159, vcc
	global_load_dwordx4 v[10:13], v[164:165], off
	global_load_dwordx4 v[14:17], v[158:159], off
	v_add_co_u32_e32 v168, vcc, s87, v158
	global_load_dwordx4 v[18:21], v[166:167], off
	s_nop 0
	v_addc_co_u32_e32 v169, vcc, 0, v159, vcc
	v_add_co_u32_e32 v170, vcc, s10, v158
	global_load_dwordx4 v[22:25], v[168:169], off
	s_nop 0
	v_addc_co_u32_e32 v171, vcc, 0, v159, vcc
	global_load_dwordx4 v[26:29], v[170:171], off
	v_add_co_u32_e32 v172, vcc, s10, v160
	s_nop 1
	v_addc_co_u32_e32 v173, vcc, 0, v161, vcc
	global_load_dwordx4 v[30:33], v[172:173], off
	global_load_dwordx4 v[70:73], v[158:159], off offset:128
	global_load_dwordx4 v[102:105], v[160:161], off offset:128
	global_load_dwordx4 v[106:109], v[166:167], off offset:128
	global_load_dwordx4 v[110:113], v[168:169], off offset:128
	global_load_dwordx4 v[114:117], v[170:171], off offset:128
	global_load_dwordx4 v[118:121], v[162:163], off offset:128
	global_load_dwordx4 v[122:125], v[164:165], off offset:128
	global_load_dwordx4 v[126:129], v[172:173], off offset:128
	s_waitcnt vmcnt(12)
	ds_write_b128 v174, v[14:17] offset:36864
	ds_write_b128 v174, v[2:5]
	s_waitcnt vmcnt(11)
	ds_write_b128 v174, v[18:21] offset:41472
	s_waitcnt vmcnt(10)
	ds_write_b128 v174, v[22:25] offset:46080
	s_waitcnt vmcnt(9)
	ds_write_b128 v174, v[26:29] offset:50688
	ds_write_b128 v174, v[6:9] offset:4608
	ds_write_b128 v174, v[10:13] offset:9216
	s_waitcnt vmcnt(8)
	ds_write_b128 v174, v[30:33] offset:13824
	s_waitcnt lgkmcnt(0)
	s_barrier
	global_load_dwordx4 v[74:77], v[162:163], off offset:256
	global_load_dwordx4 v[78:81], v[164:165], off offset:256
	global_load_dwordx4 v[94:97], v[160:161], off offset:256
	global_load_dwordx4 v[66:69], v[158:159], off offset:256
	global_load_dwordx4 v[98:101], v[172:173], off offset:256
	global_load_dwordx4 v[82:85], v[166:167], off offset:256
	global_load_dwordx4 v[86:89], v[168:169], off offset:256
	global_load_dwordx4 v[90:93], v[170:171], off offset:256
	ds_read_b128 v[50:53], v148 offset:4608
	ds_read_b128 v[54:57], v149 offset:41472
	ds_read_b128 v[18:21], v148
	ds_read_b128 v[130:133], v148 offset:32
	ds_read_b128 v[34:37], v149 offset:36864
	ds_read_b128 v[134:137], v149 offset:36896
	ds_read_b128 v[138:141], v148 offset:4640
	ds_read_b128 v[208:211], v149 offset:41504
	s_waitcnt lgkmcnt(3)
	v_mfma_f32_32x32x16_bf16 v[2:17], v[18:21], v[34:37], 0
	v_mfma_f32_32x32x16_bf16 v[18:33], v[18:21], v[54:57], 0
	v_mfma_f32_32x32x16_bf16 v[34:49], v[50:53], v[34:37], 0
	v_mfma_f32_32x32x16_bf16 v[50:65], v[50:53], v[54:57], 0
	s_waitcnt lgkmcnt(2)
	v_mfma_f32_32x32x16_bf16 v[2:17], v[130:133], v[134:137], v[2:17]
	s_waitcnt lgkmcnt(0)
	v_mfma_f32_32x32x16_bf16 v[18:33], v[130:133], v[208:211], v[18:33]
	v_mfma_f32_32x32x16_bf16 v[34:49], v[138:141], v[134:137], v[34:49]
	v_mfma_f32_32x32x16_bf16 v[50:65], v[138:141], v[208:211], v[50:65]
	ds_read_b128 v[130:133], v148 offset:64
	ds_read_b128 v[134:137], v148 offset:4672
	ds_read_b128 v[138:141], v149 offset:36928
	ds_read_b128 v[208:211], v149 offset:41536
	s_waitcnt lgkmcnt(1)
	v_mfma_f32_32x32x16_bf16 v[2:17], v[130:133], v[138:141], v[2:17]
	s_waitcnt lgkmcnt(0)
	v_mfma_f32_32x32x16_bf16 v[18:33], v[130:133], v[208:211], v[18:33]
	v_mfma_f32_32x32x16_bf16 v[34:49], v[134:137], v[138:141], v[34:49]
	v_mfma_f32_32x32x16_bf16 v[50:65], v[134:137], v[208:211], v[50:65]
	ds_read_b128 v[130:133], v148 offset:96
	ds_read_b128 v[134:137], v148 offset:4704
	ds_read_b128 v[138:141], v149 offset:36960
	ds_read_b128 v[208:211], v149 offset:41568
	s_waitcnt vmcnt(14)
	ds_write_b128 v174, v[102:105] offset:18432
	s_waitcnt vmcnt(10)
	ds_write_b128 v174, v[118:121] offset:23040
	s_waitcnt vmcnt(9)
	ds_write_b128 v174, v[122:125] offset:27648
	s_waitcnt vmcnt(8)
	ds_write_b128 v174, v[126:129] offset:32256
	ds_write_b128 v174, v[70:73] offset:55296
	ds_write_b128 v174, v[106:109] offset:59904
	ds_write_b128 v174, v[110:113] offset:64512
	ds_write_b128 v175, v[114:117] offset:32256
	global_load_dwordx4 v[70:73], v[160:161], off offset:384
	global_load_dwordx4 v[102:105], v[162:163], off offset:384
	global_load_dwordx4 v[106:109], v[164:165], off offset:384
	global_load_dwordx4 v[110:113], v[172:173], off offset:384
	global_load_dwordx4 v[114:117], v[158:159], off offset:384
	global_load_dwordx4 v[118:121], v[166:167], off offset:384
	global_load_dwordx4 v[122:125], v[168:169], off offset:384
	global_load_dwordx4 v[126:129], v[170:171], off offset:384
	s_waitcnt lgkmcnt(0)
	s_barrier
	v_mfma_f32_32x32x16_bf16 v[2:17], v[130:133], v[138:141], v[2:17]
	v_mfma_f32_32x32x16_bf16 v[18:33], v[130:133], v[208:211], v[18:33]
	v_mfma_f32_32x32x16_bf16 v[34:49], v[134:137], v[138:141], v[34:49]
	v_mfma_f32_32x32x16_bf16 v[50:65], v[134:137], v[208:211], v[50:65]
	ds_read_b128 v[130:133], v148 offset:18432
	ds_read_b128 v[134:137], v149 offset:55296
	ds_read_b128 v[138:141], v149 offset:59904
	s_waitcnt lgkmcnt(1)
	v_mfma_f32_32x32x16_bf16 v[2:17], v[130:133], v[134:137], v[2:17]
	s_waitcnt lgkmcnt(0)
	v_mfma_f32_32x32x16_bf16 v[18:33], v[130:133], v[138:141], v[18:33]
	ds_read_b128 v[130:133], v148 offset:23040
	s_waitcnt lgkmcnt(0)
	v_mfma_f32_32x32x16_bf16 v[34:49], v[130:133], v[134:137], v[34:49]
	v_mfma_f32_32x32x16_bf16 v[50:65], v[130:133], v[138:141], v[50:65]
	ds_read_b128 v[130:133], v148 offset:18464
	ds_read_b128 v[134:137], v149 offset:55328
	ds_read_b128 v[138:141], v149 offset:59936
	s_waitcnt lgkmcnt(1)
	v_mfma_f32_32x32x16_bf16 v[2:17], v[130:133], v[134:137], v[2:17]
	s_waitcnt lgkmcnt(0)
	v_mfma_f32_32x32x16_bf16 v[18:33], v[130:133], v[138:141], v[18:33]
	ds_read_b128 v[130:133], v148 offset:23072
	s_waitcnt lgkmcnt(0)
	v_mfma_f32_32x32x16_bf16 v[34:49], v[130:133], v[134:137], v[34:49]
	v_mfma_f32_32x32x16_bf16 v[50:65], v[130:133], v[138:141], v[50:65]
	ds_read_b128 v[130:133], v148 offset:18496
	ds_read_b128 v[134:137], v149 offset:55360
	ds_read_b128 v[138:141], v149 offset:59968
	s_waitcnt lgkmcnt(1)
	v_mfma_f32_32x32x16_bf16 v[2:17], v[130:133], v[134:137], v[2:17]
	s_waitcnt lgkmcnt(0)
	v_mfma_f32_32x32x16_bf16 v[18:33], v[130:133], v[138:141], v[18:33]
	ds_read_b128 v[130:133], v148 offset:23104
	s_waitcnt lgkmcnt(0)
	v_mfma_f32_32x32x16_bf16 v[34:49], v[130:133], v[134:137], v[34:49]
	v_mfma_f32_32x32x16_bf16 v[50:65], v[130:133], v[138:141], v[50:65]
	ds_read_b128 v[130:133], v148 offset:18528
	ds_read_b128 v[134:137], v149 offset:55392
	ds_read_b128 v[208:211], v148 offset:23136
	ds_read_b128 v[212:215], v149 offset:60000
	s_waitcnt vmcnt(13)
	ds_write_b128 v174, v[94:97]
	ds_write_b128 v174, v[74:77] offset:4608
	ds_write_b128 v174, v[78:81] offset:9216
	s_waitcnt vmcnt(11)
	ds_write_b128 v174, v[98:101] offset:13824
	ds_write_b128 v174, v[66:69] offset:36864
	s_waitcnt vmcnt(10)
	ds_write_b128 v174, v[82:85] offset:41472
	s_waitcnt vmcnt(9)
	ds_write_b128 v174, v[86:89] offset:46080
	s_waitcnt vmcnt(8)
	ds_write_b128 v174, v[90:93] offset:50688
	s_waitcnt lgkmcnt(0)
	s_barrier
	v_mfma_f32_32x32x16_bf16 v[2:17], v[130:133], v[134:137], v[2:17]
	v_mfma_f32_32x32x16_bf16 v[18:33], v[130:133], v[212:215], v[18:33]
	v_mfma_f32_32x32x16_bf16 v[34:49], v[208:211], v[134:137], v[34:49]
	global_load_dwordx4 v[66:69], v[160:161], off offset:512
	global_load_dwordx4 v[74:77], v[162:163], off offset:512
	global_load_dwordx4 v[78:81], v[164:165], off offset:512
	global_load_dwordx4 v[82:85], v[172:173], off offset:512
	global_load_dwordx4 v[98:101], v[158:159], off offset:512
	global_load_dwordx4 v[130:133], v[166:167], off offset:512
	global_load_dwordx4 v[134:137], v[168:169], off offset:512
	global_load_dwordx4 v[138:141], v[170:171], off offset:512
	v_mfma_f32_32x32x16_bf16 v[50:65], v[208:211], v[212:215], v[50:65]
	ds_read_b128 v[86:89], v148
	ds_read_b128 v[90:93], v149 offset:36864
	ds_read_b128 v[94:97], v149 offset:41472
	s_waitcnt lgkmcnt(1)
	v_mfma_f32_32x32x16_bf16 v[2:17], v[86:89], v[90:93], v[2:17]
	s_waitcnt lgkmcnt(0)
	v_mfma_f32_32x32x16_bf16 v[18:33], v[86:89], v[94:97], v[18:33]
	ds_read_b128 v[86:89], v148 offset:4608
	s_waitcnt lgkmcnt(0)
	v_mfma_f32_32x32x16_bf16 v[34:49], v[86:89], v[90:93], v[34:49]
	v_mfma_f32_32x32x16_bf16 v[50:65], v[86:89], v[94:97], v[50:65]
	ds_read_b128 v[86:89], v148 offset:32
	ds_read_b128 v[90:93], v149 offset:36896
	ds_read_b128 v[94:97], v149 offset:41504
	s_waitcnt lgkmcnt(1)
	v_mfma_f32_32x32x16_bf16 v[2:17], v[86:89], v[90:93], v[2:17]
	s_waitcnt lgkmcnt(0)
	v_mfma_f32_32x32x16_bf16 v[18:33], v[86:89], v[94:97], v[18:33]
	ds_read_b128 v[86:89], v148 offset:4640
	s_waitcnt lgkmcnt(0)
	v_mfma_f32_32x32x16_bf16 v[34:49], v[86:89], v[90:93], v[34:49]
	v_mfma_f32_32x32x16_bf16 v[50:65], v[86:89], v[94:97], v[50:65]
	ds_read_b128 v[86:89], v148 offset:64
	ds_read_b128 v[90:93], v149 offset:36928
	ds_read_b128 v[94:97], v149 offset:41536
	s_waitcnt lgkmcnt(1)
	v_mfma_f32_32x32x16_bf16 v[2:17], v[86:89], v[90:93], v[2:17]
	s_waitcnt lgkmcnt(0)
	v_mfma_f32_32x32x16_bf16 v[18:33], v[86:89], v[94:97], v[18:33]
	ds_read_b128 v[86:89], v148 offset:4672
	s_waitcnt lgkmcnt(0)
	v_mfma_f32_32x32x16_bf16 v[34:49], v[86:89], v[90:93], v[34:49]
	v_mfma_f32_32x32x16_bf16 v[50:65], v[86:89], v[94:97], v[50:65]
	ds_read_b128 v[86:89], v148 offset:96
	ds_read_b128 v[90:93], v149 offset:36960
	ds_read_b128 v[208:211], v148 offset:4704
	ds_read_b128 v[212:215], v149 offset:41568
	s_waitcnt vmcnt(15)
	ds_write_b128 v174, v[70:73] offset:18432
	s_waitcnt vmcnt(14)
	ds_write_b128 v174, v[102:105] offset:23040
	s_waitcnt vmcnt(13)
	ds_write_b128 v174, v[106:109] offset:27648
	s_waitcnt vmcnt(12)
	ds_write_b128 v174, v[110:113] offset:32256
	s_waitcnt vmcnt(11)
	ds_write_b128 v174, v[114:117] offset:55296
	s_waitcnt vmcnt(10)
	ds_write_b128 v174, v[118:121] offset:59904
	s_waitcnt vmcnt(9)
	ds_write_b128 v174, v[122:125] offset:64512
	s_waitcnt vmcnt(8)
	ds_write_b128 v175, v[126:129] offset:32256
	s_waitcnt lgkmcnt(0)
	s_barrier
	v_mfma_f32_32x32x16_bf16 v[2:17], v[86:89], v[90:93], v[2:17]
	v_mfma_f32_32x32x16_bf16 v[18:33], v[86:89], v[212:215], v[18:33]
	v_mfma_f32_32x32x16_bf16 v[34:49], v[208:211], v[90:93], v[34:49]
	global_load_dwordx4 v[70:73], v[160:161], off offset:640
	global_load_dwordx4 v[86:89], v[162:163], off offset:640
	global_load_dwordx4 v[90:93], v[164:165], off offset:640
	global_load_dwordx4 v[94:97], v[172:173], off offset:640
	global_load_dwordx4 v[102:105], v[158:159], off offset:640
	global_load_dwordx4 v[106:109], v[166:167], off offset:640
	global_load_dwordx4 v[110:113], v[168:169], off offset:640
	global_load_dwordx4 v[114:117], v[170:171], off offset:640
	v_mfma_f32_32x32x16_bf16 v[50:65], v[208:211], v[212:215], v[50:65]
	ds_read_b128 v[118:121], v148 offset:18432
	ds_read_b128 v[122:125], v149 offset:55296
	ds_read_b128 v[126:129], v149 offset:59904
	s_waitcnt lgkmcnt(1)
	v_mfma_f32_32x32x16_bf16 v[2:17], v[118:121], v[122:125], v[2:17]
	s_waitcnt lgkmcnt(0)
	v_mfma_f32_32x32x16_bf16 v[18:33], v[118:121], v[126:129], v[18:33]
	ds_read_b128 v[118:121], v148 offset:23040
	s_waitcnt lgkmcnt(0)
	v_mfma_f32_32x32x16_bf16 v[34:49], v[118:121], v[122:125], v[34:49]
	v_mfma_f32_32x32x16_bf16 v[50:65], v[118:121], v[126:129], v[50:65]
	ds_read_b128 v[118:121], v148 offset:18464
	ds_read_b128 v[122:125], v149 offset:55328
	ds_read_b128 v[126:129], v149 offset:59936
	s_waitcnt lgkmcnt(1)
	v_mfma_f32_32x32x16_bf16 v[2:17], v[118:121], v[122:125], v[2:17]
	s_waitcnt lgkmcnt(0)
	v_mfma_f32_32x32x16_bf16 v[18:33], v[118:121], v[126:129], v[18:33]
	ds_read_b128 v[118:121], v148 offset:23072
	s_waitcnt lgkmcnt(0)
	v_mfma_f32_32x32x16_bf16 v[34:49], v[118:121], v[122:125], v[34:49]
	v_mfma_f32_32x32x16_bf16 v[50:65], v[118:121], v[126:129], v[50:65]
	ds_read_b128 v[118:121], v148 offset:18496
	ds_read_b128 v[122:125], v149 offset:55360
	ds_read_b128 v[126:129], v149 offset:59968
	s_waitcnt lgkmcnt(1)
	v_mfma_f32_32x32x16_bf16 v[2:17], v[118:121], v[122:125], v[2:17]
	s_waitcnt lgkmcnt(0)
	v_mfma_f32_32x32x16_bf16 v[18:33], v[118:121], v[126:129], v[18:33]
	ds_read_b128 v[118:121], v148 offset:23104
	s_waitcnt lgkmcnt(0)
	v_mfma_f32_32x32x16_bf16 v[34:49], v[118:121], v[122:125], v[34:49]
	v_mfma_f32_32x32x16_bf16 v[50:65], v[118:121], v[126:129], v[50:65]
	ds_read_b128 v[118:121], v148 offset:18528
	ds_read_b128 v[122:125], v149 offset:55392
	ds_read_b128 v[208:211], v148 offset:23136
	ds_read_b128 v[212:215], v149 offset:60000
	s_waitcnt vmcnt(15)
	ds_write_b128 v174, v[66:69]
	s_waitcnt vmcnt(14)
	ds_write_b128 v174, v[74:77] offset:4608
	s_waitcnt vmcnt(13)
	ds_write_b128 v174, v[78:81] offset:9216
	s_waitcnt vmcnt(12)
	ds_write_b128 v174, v[82:85] offset:13824
	s_waitcnt vmcnt(11)
	ds_write_b128 v174, v[98:101] offset:36864
	s_waitcnt vmcnt(10)
	ds_write_b128 v174, v[130:133] offset:41472
	s_waitcnt vmcnt(9)
	ds_write_b128 v174, v[134:137] offset:46080
	s_waitcnt vmcnt(8)
	ds_write_b128 v174, v[138:141] offset:50688
	s_waitcnt lgkmcnt(0)
	s_barrier
	v_mfma_f32_32x32x16_bf16 v[2:17], v[118:121], v[122:125], v[2:17]
	v_mfma_f32_32x32x16_bf16 v[18:33], v[118:121], v[212:215], v[18:33]
	v_mfma_f32_32x32x16_bf16 v[34:49], v[208:211], v[122:125], v[34:49]
	global_load_dwordx4 v[66:69], v[160:161], off offset:768
	global_load_dwordx4 v[74:77], v[162:163], off offset:768
	global_load_dwordx4 v[78:81], v[164:165], off offset:768
	global_load_dwordx4 v[82:85], v[172:173], off offset:768
	global_load_dwordx4 v[98:101], v[158:159], off offset:768
	global_load_dwordx4 v[118:121], v[166:167], off offset:768
	global_load_dwordx4 v[122:125], v[168:169], off offset:768
	global_load_dwordx4 v[126:129], v[170:171], off offset:768
	v_mfma_f32_32x32x16_bf16 v[50:65], v[208:211], v[212:215], v[50:65]
	ds_read_b128 v[130:133], v148
	ds_read_b128 v[134:137], v149 offset:36864
	ds_read_b128 v[138:141], v149 offset:41472
	s_waitcnt lgkmcnt(1)
	v_mfma_f32_32x32x16_bf16 v[2:17], v[130:133], v[134:137], v[2:17]
	s_waitcnt lgkmcnt(0)
	v_mfma_f32_32x32x16_bf16 v[18:33], v[130:133], v[138:141], v[18:33]
	ds_read_b128 v[130:133], v148 offset:4608
	s_waitcnt lgkmcnt(0)
	v_mfma_f32_32x32x16_bf16 v[34:49], v[130:133], v[134:137], v[34:49]
	v_mfma_f32_32x32x16_bf16 v[50:65], v[130:133], v[138:141], v[50:65]
	ds_read_b128 v[130:133], v148 offset:32
	ds_read_b128 v[134:137], v149 offset:36896
	ds_read_b128 v[138:141], v149 offset:41504
	s_waitcnt lgkmcnt(1)
	v_mfma_f32_32x32x16_bf16 v[2:17], v[130:133], v[134:137], v[2:17]
	s_waitcnt lgkmcnt(0)
	v_mfma_f32_32x32x16_bf16 v[18:33], v[130:133], v[138:141], v[18:33]
	ds_read_b128 v[130:133], v148 offset:4640
	s_waitcnt lgkmcnt(0)
	v_mfma_f32_32x32x16_bf16 v[34:49], v[130:133], v[134:137], v[34:49]
	v_mfma_f32_32x32x16_bf16 v[50:65], v[130:133], v[138:141], v[50:65]
	ds_read_b128 v[130:133], v148 offset:64
	ds_read_b128 v[134:137], v149 offset:36928
	ds_read_b128 v[138:141], v149 offset:41536
	s_waitcnt lgkmcnt(1)
	v_mfma_f32_32x32x16_bf16 v[2:17], v[130:133], v[134:137], v[2:17]
	s_waitcnt lgkmcnt(0)
	v_mfma_f32_32x32x16_bf16 v[18:33], v[130:133], v[138:141], v[18:33]
	ds_read_b128 v[130:133], v148 offset:4672
	s_waitcnt lgkmcnt(0)
	v_mfma_f32_32x32x16_bf16 v[34:49], v[130:133], v[134:137], v[34:49]
	v_mfma_f32_32x32x16_bf16 v[50:65], v[130:133], v[138:141], v[50:65]
	ds_read_b128 v[130:133], v148 offset:96
	ds_read_b128 v[134:137], v149 offset:36960
	ds_read_b128 v[138:141], v148 offset:4704
	ds_read_b128 v[208:211], v149 offset:41568
	s_waitcnt vmcnt(15)
	ds_write_b128 v174, v[70:73] offset:18432
	s_waitcnt vmcnt(14)
	ds_write_b128 v174, v[86:89] offset:23040
	s_waitcnt vmcnt(13)
	ds_write_b128 v174, v[90:93] offset:27648
	s_waitcnt vmcnt(12)
	ds_write_b128 v174, v[94:97] offset:32256
	s_waitcnt vmcnt(11)
	ds_write_b128 v174, v[102:105] offset:55296
	s_waitcnt vmcnt(10)
	ds_write_b128 v174, v[106:109] offset:59904
	s_waitcnt vmcnt(9)
	ds_write_b128 v174, v[110:113] offset:64512
	s_waitcnt vmcnt(8)
	ds_write_b128 v175, v[114:117] offset:32256
	global_load_dwordx4 v[70:73], v[160:161], off offset:896
	global_load_dwordx4 v[86:89], v[162:163], off offset:896
	global_load_dwordx4 v[90:93], v[164:165], off offset:896
	global_load_dwordx4 v[94:97], v[172:173], off offset:896
	global_load_dwordx4 v[102:105], v[158:159], off offset:896
	global_load_dwordx4 v[106:109], v[166:167], off offset:896
	global_load_dwordx4 v[110:113], v[168:169], off offset:896
	global_load_dwordx4 v[114:117], v[170:171], off offset:896
	s_waitcnt lgkmcnt(0)
	s_barrier
	v_mfma_f32_32x32x16_bf16 v[2:17], v[130:133], v[134:137], v[2:17]
	v_mfma_f32_32x32x16_bf16 v[18:33], v[130:133], v[208:211], v[18:33]
	v_mfma_f32_32x32x16_bf16 v[34:49], v[138:141], v[134:137], v[34:49]
	v_mfma_f32_32x32x16_bf16 v[50:65], v[138:141], v[208:211], v[50:65]
	ds_read_b128 v[130:133], v148 offset:18432
	ds_read_b128 v[134:137], v149 offset:55296
	ds_read_b128 v[138:141], v149 offset:59904
	s_waitcnt lgkmcnt(1)
	v_mfma_f32_32x32x16_bf16 v[2:17], v[130:133], v[134:137], v[2:17]
	s_waitcnt lgkmcnt(0)
	v_mfma_f32_32x32x16_bf16 v[18:33], v[130:133], v[138:141], v[18:33]
	ds_read_b128 v[130:133], v148 offset:23040
	s_waitcnt lgkmcnt(0)
	v_mfma_f32_32x32x16_bf16 v[34:49], v[130:133], v[134:137], v[34:49]
	v_mfma_f32_32x32x16_bf16 v[50:65], v[130:133], v[138:141], v[50:65]
	ds_read_b128 v[130:133], v148 offset:18464
	ds_read_b128 v[134:137], v149 offset:55328
	ds_read_b128 v[138:141], v149 offset:59936
	s_waitcnt lgkmcnt(1)
	v_mfma_f32_32x32x16_bf16 v[2:17], v[130:133], v[134:137], v[2:17]
	s_waitcnt lgkmcnt(0)
	v_mfma_f32_32x32x16_bf16 v[18:33], v[130:133], v[138:141], v[18:33]
	ds_read_b128 v[130:133], v148 offset:23072
	s_waitcnt lgkmcnt(0)
	v_mfma_f32_32x32x16_bf16 v[34:49], v[130:133], v[134:137], v[34:49]
	v_mfma_f32_32x32x16_bf16 v[50:65], v[130:133], v[138:141], v[50:65]
	ds_read_b128 v[130:133], v148 offset:18496
	ds_read_b128 v[134:137], v149 offset:55360
	ds_read_b128 v[138:141], v149 offset:59968
	s_waitcnt lgkmcnt(1)
	v_mfma_f32_32x32x16_bf16 v[2:17], v[130:133], v[134:137], v[2:17]
	s_waitcnt lgkmcnt(0)
	v_mfma_f32_32x32x16_bf16 v[18:33], v[130:133], v[138:141], v[18:33]
	ds_read_b128 v[130:133], v148 offset:23104
	s_waitcnt lgkmcnt(0)
	v_mfma_f32_32x32x16_bf16 v[34:49], v[130:133], v[134:137], v[34:49]
	v_mfma_f32_32x32x16_bf16 v[50:65], v[130:133], v[138:141], v[50:65]
	ds_read_b128 v[130:133], v148 offset:18528
	ds_read_b128 v[134:137], v149 offset:55392
	ds_read_b128 v[138:141], v148 offset:23136
	ds_read_b128 v[208:211], v149 offset:60000
	s_waitcnt vmcnt(15)
	ds_write_b128 v174, v[66:69]
	s_waitcnt vmcnt(14)
	ds_write_b128 v174, v[74:77] offset:4608
	s_waitcnt vmcnt(13)
	ds_write_b128 v174, v[78:81] offset:9216
	s_waitcnt vmcnt(12)
	ds_write_b128 v174, v[82:85] offset:13824
	s_waitcnt vmcnt(11)
	ds_write_b128 v174, v[98:101] offset:36864
	s_waitcnt vmcnt(10)
	ds_write_b128 v174, v[118:121] offset:41472
	s_waitcnt vmcnt(9)
	ds_write_b128 v174, v[122:125] offset:46080
	s_waitcnt vmcnt(8)
	ds_write_b128 v174, v[126:129] offset:50688
	global_load_dwordx4 v[66:69], v[160:161], off offset:1024
	global_load_dwordx4 v[74:77], v[162:163], off offset:1024
	global_load_dwordx4 v[78:81], v[164:165], off offset:1024
	global_load_dwordx4 v[82:85], v[172:173], off offset:1024
	global_load_dwordx4 v[98:101], v[158:159], off offset:1024
	global_load_dwordx4 v[118:121], v[166:167], off offset:1024
	global_load_dwordx4 v[122:125], v[168:169], off offset:1024
	global_load_dwordx4 v[126:129], v[170:171], off offset:1024
	s_waitcnt lgkmcnt(0)
	s_barrier
	v_mfma_f32_32x32x16_bf16 v[2:17], v[130:133], v[134:137], v[2:17]
	v_mfma_f32_32x32x16_bf16 v[18:33], v[130:133], v[208:211], v[18:33]
	v_mfma_f32_32x32x16_bf16 v[34:49], v[138:141], v[134:137], v[34:49]
	v_mfma_f32_32x32x16_bf16 v[50:65], v[138:141], v[208:211], v[50:65]
	ds_read_b128 v[130:133], v148
	ds_read_b128 v[134:137], v149 offset:36864
	ds_read_b128 v[138:141], v149 offset:41472
	s_waitcnt lgkmcnt(1)
	v_mfma_f32_32x32x16_bf16 v[2:17], v[130:133], v[134:137], v[2:17]
	s_waitcnt lgkmcnt(0)
	v_mfma_f32_32x32x16_bf16 v[18:33], v[130:133], v[138:141], v[18:33]
	ds_read_b128 v[130:133], v148 offset:4608
	s_waitcnt lgkmcnt(0)
	v_mfma_f32_32x32x16_bf16 v[34:49], v[130:133], v[134:137], v[34:49]
	v_mfma_f32_32x32x16_bf16 v[50:65], v[130:133], v[138:141], v[50:65]
	ds_read_b128 v[130:133], v148 offset:32
	ds_read_b128 v[134:137], v149 offset:36896
	ds_read_b128 v[138:141], v149 offset:41504
	s_waitcnt lgkmcnt(1)
	v_mfma_f32_32x32x16_bf16 v[2:17], v[130:133], v[134:137], v[2:17]
	s_waitcnt lgkmcnt(0)
	v_mfma_f32_32x32x16_bf16 v[18:33], v[130:133], v[138:141], v[18:33]
	ds_read_b128 v[130:133], v148 offset:4640
	s_waitcnt lgkmcnt(0)
	v_mfma_f32_32x32x16_bf16 v[34:49], v[130:133], v[134:137], v[34:49]
	v_mfma_f32_32x32x16_bf16 v[50:65], v[130:133], v[138:141], v[50:65]
	ds_read_b128 v[130:133], v148 offset:64
	ds_read_b128 v[134:137], v149 offset:36928
	ds_read_b128 v[138:141], v149 offset:41536
	s_waitcnt lgkmcnt(1)
	v_mfma_f32_32x32x16_bf16 v[2:17], v[130:133], v[134:137], v[2:17]
	s_waitcnt lgkmcnt(0)
	v_mfma_f32_32x32x16_bf16 v[18:33], v[130:133], v[138:141], v[18:33]
	ds_read_b128 v[130:133], v148 offset:4672
	s_waitcnt lgkmcnt(0)
	v_mfma_f32_32x32x16_bf16 v[34:49], v[130:133], v[134:137], v[34:49]
	v_mfma_f32_32x32x16_bf16 v[50:65], v[130:133], v[138:141], v[50:65]
	ds_read_b128 v[130:133], v148 offset:96
	ds_read_b128 v[134:137], v149 offset:36960
	ds_read_b128 v[138:141], v148 offset:4704
	ds_read_b128 v[208:211], v149 offset:41568
	s_waitcnt vmcnt(15)
	ds_write_b128 v174, v[70:73] offset:18432
	s_waitcnt vmcnt(14)
	ds_write_b128 v174, v[86:89] offset:23040
	s_waitcnt vmcnt(13)
	ds_write_b128 v174, v[90:93] offset:27648
	s_waitcnt vmcnt(12)
	ds_write_b128 v174, v[94:97] offset:32256
	s_waitcnt vmcnt(11)
	ds_write_b128 v174, v[102:105] offset:55296
	s_waitcnt vmcnt(10)
	ds_write_b128 v174, v[106:109] offset:59904
	s_waitcnt vmcnt(9)
	ds_write_b128 v174, v[110:113] offset:64512
	s_waitcnt vmcnt(8)
	ds_write_b128 v175, v[114:117] offset:32256
	global_load_dwordx4 v[70:73], v[160:161], off offset:1152
	global_load_dwordx4 v[86:89], v[162:163], off offset:1152
	global_load_dwordx4 v[90:93], v[164:165], off offset:1152
	global_load_dwordx4 v[94:97], v[172:173], off offset:1152
	global_load_dwordx4 v[102:105], v[158:159], off offset:1152
	global_load_dwordx4 v[106:109], v[166:167], off offset:1152
	global_load_dwordx4 v[110:113], v[168:169], off offset:1152
	global_load_dwordx4 v[114:117], v[170:171], off offset:1152
	s_waitcnt lgkmcnt(0)
	s_barrier
	v_mfma_f32_32x32x16_bf16 v[2:17], v[130:133], v[134:137], v[2:17]
	v_mfma_f32_32x32x16_bf16 v[18:33], v[130:133], v[208:211], v[18:33]
	v_mfma_f32_32x32x16_bf16 v[34:49], v[138:141], v[134:137], v[34:49]
	v_mfma_f32_32x32x16_bf16 v[50:65], v[138:141], v[208:211], v[50:65]
	ds_read_b128 v[130:133], v148 offset:18432
	ds_read_b128 v[134:137], v149 offset:55296
	ds_read_b128 v[138:141], v149 offset:59904
	s_waitcnt lgkmcnt(1)
	v_mfma_f32_32x32x16_bf16 v[2:17], v[130:133], v[134:137], v[2:17]
	s_waitcnt lgkmcnt(0)
	v_mfma_f32_32x32x16_bf16 v[18:33], v[130:133], v[138:141], v[18:33]
	ds_read_b128 v[130:133], v148 offset:23040
	s_waitcnt lgkmcnt(0)
	v_mfma_f32_32x32x16_bf16 v[34:49], v[130:133], v[134:137], v[34:49]
	v_mfma_f32_32x32x16_bf16 v[50:65], v[130:133], v[138:141], v[50:65]
	ds_read_b128 v[130:133], v148 offset:18464
	ds_read_b128 v[134:137], v149 offset:55328
	ds_read_b128 v[138:141], v149 offset:59936
	s_waitcnt lgkmcnt(1)
	v_mfma_f32_32x32x16_bf16 v[2:17], v[130:133], v[134:137], v[2:17]
	s_waitcnt lgkmcnt(0)
	v_mfma_f32_32x32x16_bf16 v[18:33], v[130:133], v[138:141], v[18:33]
	ds_read_b128 v[130:133], v148 offset:23072
	s_waitcnt lgkmcnt(0)
	v_mfma_f32_32x32x16_bf16 v[34:49], v[130:133], v[134:137], v[34:49]
	v_mfma_f32_32x32x16_bf16 v[50:65], v[130:133], v[138:141], v[50:65]
	ds_read_b128 v[130:133], v148 offset:18496
	ds_read_b128 v[134:137], v149 offset:55360
	ds_read_b128 v[138:141], v149 offset:59968
	s_waitcnt lgkmcnt(1)
	v_mfma_f32_32x32x16_bf16 v[2:17], v[130:133], v[134:137], v[2:17]
	s_waitcnt lgkmcnt(0)
	v_mfma_f32_32x32x16_bf16 v[18:33], v[130:133], v[138:141], v[18:33]
	ds_read_b128 v[130:133], v148 offset:23104
	s_waitcnt lgkmcnt(0)
	v_mfma_f32_32x32x16_bf16 v[34:49], v[130:133], v[134:137], v[34:49]
	v_mfma_f32_32x32x16_bf16 v[50:65], v[130:133], v[138:141], v[50:65]
	ds_read_b128 v[130:133], v148 offset:18528
	ds_read_b128 v[134:137], v149 offset:55392
	ds_read_b128 v[138:141], v148 offset:23136
	ds_read_b128 v[208:211], v149 offset:60000
	s_waitcnt vmcnt(15)
	ds_write_b128 v174, v[66:69]
	s_waitcnt vmcnt(14)
	ds_write_b128 v174, v[74:77] offset:4608
	s_waitcnt vmcnt(13)
	ds_write_b128 v174, v[78:81] offset:9216
	s_waitcnt vmcnt(12)
	ds_write_b128 v174, v[82:85] offset:13824
	s_waitcnt vmcnt(11)
	ds_write_b128 v174, v[98:101] offset:36864
	s_waitcnt vmcnt(10)
	ds_write_b128 v174, v[118:121] offset:41472
	s_waitcnt vmcnt(9)
	ds_write_b128 v174, v[122:125] offset:46080
	s_waitcnt vmcnt(8)
	ds_write_b128 v174, v[126:129] offset:50688
	global_load_dwordx4 v[66:69], v[160:161], off offset:1280
	global_load_dwordx4 v[74:77], v[162:163], off offset:1280
	global_load_dwordx4 v[78:81], v[164:165], off offset:1280
	global_load_dwordx4 v[82:85], v[172:173], off offset:1280
	global_load_dwordx4 v[98:101], v[158:159], off offset:1280
	global_load_dwordx4 v[118:121], v[166:167], off offset:1280
	global_load_dwordx4 v[122:125], v[168:169], off offset:1280
	global_load_dwordx4 v[126:129], v[170:171], off offset:1280
	s_waitcnt lgkmcnt(0)
	s_barrier
	v_mfma_f32_32x32x16_bf16 v[2:17], v[130:133], v[134:137], v[2:17]
	v_mfma_f32_32x32x16_bf16 v[18:33], v[130:133], v[208:211], v[18:33]
	v_mfma_f32_32x32x16_bf16 v[34:49], v[138:141], v[134:137], v[34:49]
	v_mfma_f32_32x32x16_bf16 v[50:65], v[138:141], v[208:211], v[50:65]
	ds_read_b128 v[130:133], v148
	ds_read_b128 v[134:137], v149 offset:36864
	ds_read_b128 v[138:141], v149 offset:41472
	s_waitcnt lgkmcnt(1)
	v_mfma_f32_32x32x16_bf16 v[2:17], v[130:133], v[134:137], v[2:17]
	s_waitcnt lgkmcnt(0)
	v_mfma_f32_32x32x16_bf16 v[18:33], v[130:133], v[138:141], v[18:33]
	ds_read_b128 v[130:133], v148 offset:4608
	s_waitcnt lgkmcnt(0)
	v_mfma_f32_32x32x16_bf16 v[34:49], v[130:133], v[134:137], v[34:49]
	v_mfma_f32_32x32x16_bf16 v[50:65], v[130:133], v[138:141], v[50:65]
	ds_read_b128 v[130:133], v148 offset:32
	ds_read_b128 v[134:137], v149 offset:36896
	ds_read_b128 v[138:141], v149 offset:41504
	s_waitcnt lgkmcnt(1)
	v_mfma_f32_32x32x16_bf16 v[2:17], v[130:133], v[134:137], v[2:17]
	s_waitcnt lgkmcnt(0)
	v_mfma_f32_32x32x16_bf16 v[18:33], v[130:133], v[138:141], v[18:33]
	ds_read_b128 v[130:133], v148 offset:4640
	s_waitcnt lgkmcnt(0)
	v_mfma_f32_32x32x16_bf16 v[34:49], v[130:133], v[134:137], v[34:49]
	v_mfma_f32_32x32x16_bf16 v[50:65], v[130:133], v[138:141], v[50:65]
	ds_read_b128 v[130:133], v148 offset:64
	ds_read_b128 v[134:137], v149 offset:36928
	ds_read_b128 v[138:141], v149 offset:41536
	s_waitcnt lgkmcnt(1)
	v_mfma_f32_32x32x16_bf16 v[2:17], v[130:133], v[134:137], v[2:17]
	s_waitcnt lgkmcnt(0)
	v_mfma_f32_32x32x16_bf16 v[18:33], v[130:133], v[138:141], v[18:33]
	ds_read_b128 v[130:133], v148 offset:4672
	s_waitcnt lgkmcnt(0)
	v_mfma_f32_32x32x16_bf16 v[34:49], v[130:133], v[134:137], v[34:49]
	v_mfma_f32_32x32x16_bf16 v[50:65], v[130:133], v[138:141], v[50:65]
	ds_read_b128 v[130:133], v148 offset:96
	ds_read_b128 v[134:137], v149 offset:36960
	ds_read_b128 v[138:141], v148 offset:4704
	ds_read_b128 v[208:211], v149 offset:41568
	s_waitcnt vmcnt(15)
	ds_write_b128 v174, v[70:73] offset:18432
	s_waitcnt vmcnt(14)
	ds_write_b128 v174, v[86:89] offset:23040
	s_waitcnt vmcnt(13)
	ds_write_b128 v174, v[90:93] offset:27648
	s_waitcnt vmcnt(12)
	ds_write_b128 v174, v[94:97] offset:32256
	s_waitcnt vmcnt(11)
	ds_write_b128 v174, v[102:105] offset:55296
	s_waitcnt vmcnt(10)
	ds_write_b128 v174, v[106:109] offset:59904
	s_waitcnt vmcnt(9)
	ds_write_b128 v174, v[110:113] offset:64512
	s_waitcnt vmcnt(8)
	ds_write_b128 v175, v[114:117] offset:32256
	global_load_dwordx4 v[70:73], v[160:161], off offset:1408
	global_load_dwordx4 v[86:89], v[162:163], off offset:1408
	global_load_dwordx4 v[90:93], v[164:165], off offset:1408
	global_load_dwordx4 v[94:97], v[172:173], off offset:1408
	global_load_dwordx4 v[102:105], v[158:159], off offset:1408
	global_load_dwordx4 v[106:109], v[166:167], off offset:1408
	global_load_dwordx4 v[110:113], v[168:169], off offset:1408
	global_load_dwordx4 v[114:117], v[170:171], off offset:1408
	s_waitcnt lgkmcnt(0)
	s_barrier
	v_mfma_f32_32x32x16_bf16 v[2:17], v[130:133], v[134:137], v[2:17]
	v_mfma_f32_32x32x16_bf16 v[18:33], v[130:133], v[208:211], v[18:33]
	v_mfma_f32_32x32x16_bf16 v[34:49], v[138:141], v[134:137], v[34:49]
	v_mfma_f32_32x32x16_bf16 v[50:65], v[138:141], v[208:211], v[50:65]
	ds_read_b128 v[130:133], v148 offset:18432
	ds_read_b128 v[134:137], v149 offset:55296
	ds_read_b128 v[138:141], v149 offset:59904
	s_waitcnt lgkmcnt(1)
	v_mfma_f32_32x32x16_bf16 v[2:17], v[130:133], v[134:137], v[2:17]
	s_waitcnt lgkmcnt(0)
	v_mfma_f32_32x32x16_bf16 v[18:33], v[130:133], v[138:141], v[18:33]
	ds_read_b128 v[130:133], v148 offset:23040
	s_waitcnt lgkmcnt(0)
	v_mfma_f32_32x32x16_bf16 v[34:49], v[130:133], v[134:137], v[34:49]
	v_mfma_f32_32x32x16_bf16 v[50:65], v[130:133], v[138:141], v[50:65]
	ds_read_b128 v[130:133], v148 offset:18464
	ds_read_b128 v[134:137], v149 offset:55328
	ds_read_b128 v[138:141], v149 offset:59936
	s_waitcnt lgkmcnt(1)
	v_mfma_f32_32x32x16_bf16 v[2:17], v[130:133], v[134:137], v[2:17]
	s_waitcnt lgkmcnt(0)
	v_mfma_f32_32x32x16_bf16 v[18:33], v[130:133], v[138:141], v[18:33]
	ds_read_b128 v[130:133], v148 offset:23072
	s_waitcnt lgkmcnt(0)
	v_mfma_f32_32x32x16_bf16 v[34:49], v[130:133], v[134:137], v[34:49]
	v_mfma_f32_32x32x16_bf16 v[50:65], v[130:133], v[138:141], v[50:65]
	ds_read_b128 v[130:133], v148 offset:18496
	ds_read_b128 v[134:137], v149 offset:55360
	ds_read_b128 v[138:141], v149 offset:59968
	s_waitcnt lgkmcnt(1)
	v_mfma_f32_32x32x16_bf16 v[2:17], v[130:133], v[134:137], v[2:17]
	s_waitcnt lgkmcnt(0)
	v_mfma_f32_32x32x16_bf16 v[18:33], v[130:133], v[138:141], v[18:33]
	ds_read_b128 v[130:133], v148 offset:23104
	s_waitcnt lgkmcnt(0)
	v_mfma_f32_32x32x16_bf16 v[34:49], v[130:133], v[134:137], v[34:49]
	v_mfma_f32_32x32x16_bf16 v[50:65], v[130:133], v[138:141], v[50:65]
	ds_read_b128 v[130:133], v148 offset:18528
	ds_read_b128 v[134:137], v149 offset:55392
	ds_read_b128 v[138:141], v148 offset:23136
	ds_read_b128 v[208:211], v149 offset:60000
	s_waitcnt vmcnt(15)
	ds_write_b128 v174, v[66:69]
	s_waitcnt vmcnt(14)
	ds_write_b128 v174, v[74:77] offset:4608
	s_waitcnt vmcnt(13)
	ds_write_b128 v174, v[78:81] offset:9216
	s_waitcnt vmcnt(12)
	ds_write_b128 v174, v[82:85] offset:13824
	s_waitcnt vmcnt(11)
	ds_write_b128 v174, v[98:101] offset:36864
	s_waitcnt vmcnt(10)
	ds_write_b128 v174, v[118:121] offset:41472
	s_waitcnt vmcnt(9)
	ds_write_b128 v174, v[122:125] offset:46080
	s_waitcnt vmcnt(8)
	ds_write_b128 v174, v[126:129] offset:50688
	global_load_dwordx4 v[66:69], v[160:161], off offset:1536
	global_load_dwordx4 v[74:77], v[162:163], off offset:1536
	global_load_dwordx4 v[78:81], v[164:165], off offset:1536
	global_load_dwordx4 v[82:85], v[172:173], off offset:1536
	global_load_dwordx4 v[98:101], v[158:159], off offset:1536
	global_load_dwordx4 v[118:121], v[166:167], off offset:1536
	global_load_dwordx4 v[122:125], v[168:169], off offset:1536
	global_load_dwordx4 v[126:129], v[170:171], off offset:1536
	s_waitcnt lgkmcnt(0)
	s_barrier
	v_mfma_f32_32x32x16_bf16 v[2:17], v[130:133], v[134:137], v[2:17]
	v_mfma_f32_32x32x16_bf16 v[18:33], v[130:133], v[208:211], v[18:33]
	v_mfma_f32_32x32x16_bf16 v[34:49], v[138:141], v[134:137], v[34:49]
	v_mfma_f32_32x32x16_bf16 v[50:65], v[138:141], v[208:211], v[50:65]
	ds_read_b128 v[130:133], v148
	ds_read_b128 v[134:137], v149 offset:36864
	ds_read_b128 v[138:141], v149 offset:41472
	s_waitcnt lgkmcnt(1)
	v_mfma_f32_32x32x16_bf16 v[2:17], v[130:133], v[134:137], v[2:17]
	s_waitcnt lgkmcnt(0)
	v_mfma_f32_32x32x16_bf16 v[18:33], v[130:133], v[138:141], v[18:33]
	ds_read_b128 v[130:133], v148 offset:4608
	s_waitcnt lgkmcnt(0)
	v_mfma_f32_32x32x16_bf16 v[34:49], v[130:133], v[134:137], v[34:49]
	v_mfma_f32_32x32x16_bf16 v[50:65], v[130:133], v[138:141], v[50:65]
	ds_read_b128 v[130:133], v148 offset:32
	ds_read_b128 v[134:137], v149 offset:36896
	ds_read_b128 v[138:141], v149 offset:41504
	s_waitcnt lgkmcnt(1)
	v_mfma_f32_32x32x16_bf16 v[2:17], v[130:133], v[134:137], v[2:17]
	s_waitcnt lgkmcnt(0)
	v_mfma_f32_32x32x16_bf16 v[18:33], v[130:133], v[138:141], v[18:33]
	ds_read_b128 v[130:133], v148 offset:4640
	s_waitcnt lgkmcnt(0)
	v_mfma_f32_32x32x16_bf16 v[34:49], v[130:133], v[134:137], v[34:49]
	v_mfma_f32_32x32x16_bf16 v[50:65], v[130:133], v[138:141], v[50:65]
	ds_read_b128 v[130:133], v148 offset:64
	ds_read_b128 v[134:137], v149 offset:36928
	ds_read_b128 v[138:141], v149 offset:41536
	s_waitcnt lgkmcnt(1)
	v_mfma_f32_32x32x16_bf16 v[2:17], v[130:133], v[134:137], v[2:17]
	s_waitcnt lgkmcnt(0)
	v_mfma_f32_32x32x16_bf16 v[18:33], v[130:133], v[138:141], v[18:33]
	ds_read_b128 v[130:133], v148 offset:4672
	s_waitcnt lgkmcnt(0)
	v_mfma_f32_32x32x16_bf16 v[34:49], v[130:133], v[134:137], v[34:49]
	v_mfma_f32_32x32x16_bf16 v[50:65], v[130:133], v[138:141], v[50:65]
	ds_read_b128 v[130:133], v148 offset:96
	ds_read_b128 v[134:137], v149 offset:36960
	ds_read_b128 v[138:141], v148 offset:4704
	ds_read_b128 v[208:211], v149 offset:41568
	s_waitcnt vmcnt(15)
	ds_write_b128 v174, v[70:73] offset:18432
	s_waitcnt vmcnt(14)
	ds_write_b128 v174, v[86:89] offset:23040
	s_waitcnt vmcnt(13)
	ds_write_b128 v174, v[90:93] offset:27648
	s_waitcnt vmcnt(12)
	ds_write_b128 v174, v[94:97] offset:32256
	s_waitcnt vmcnt(11)
	ds_write_b128 v174, v[102:105] offset:55296
	s_waitcnt vmcnt(10)
	ds_write_b128 v174, v[106:109] offset:59904
	s_waitcnt vmcnt(9)
	ds_write_b128 v174, v[110:113] offset:64512
	s_waitcnt vmcnt(8)
	ds_write_b128 v175, v[114:117] offset:32256
	global_load_dwordx4 v[70:73], v[160:161], off offset:1664
	global_load_dwordx4 v[86:89], v[162:163], off offset:1664
	global_load_dwordx4 v[90:93], v[164:165], off offset:1664
	global_load_dwordx4 v[94:97], v[172:173], off offset:1664
	global_load_dwordx4 v[102:105], v[158:159], off offset:1664
	global_load_dwordx4 v[106:109], v[166:167], off offset:1664
	global_load_dwordx4 v[110:113], v[168:169], off offset:1664
	global_load_dwordx4 v[114:117], v[170:171], off offset:1664
	s_waitcnt lgkmcnt(0)
	s_barrier
	v_mfma_f32_32x32x16_bf16 v[2:17], v[130:133], v[134:137], v[2:17]
	v_mfma_f32_32x32x16_bf16 v[18:33], v[130:133], v[208:211], v[18:33]
	v_mfma_f32_32x32x16_bf16 v[34:49], v[138:141], v[134:137], v[34:49]
	v_mfma_f32_32x32x16_bf16 v[50:65], v[138:141], v[208:211], v[50:65]
	ds_read_b128 v[130:133], v148 offset:18432
	ds_read_b128 v[134:137], v149 offset:55296
	ds_read_b128 v[138:141], v149 offset:59904
	s_waitcnt lgkmcnt(1)
	v_mfma_f32_32x32x16_bf16 v[2:17], v[130:133], v[134:137], v[2:17]
	s_waitcnt lgkmcnt(0)
	v_mfma_f32_32x32x16_bf16 v[18:33], v[130:133], v[138:141], v[18:33]
	ds_read_b128 v[130:133], v148 offset:23040
	s_waitcnt lgkmcnt(0)
	v_mfma_f32_32x32x16_bf16 v[34:49], v[130:133], v[134:137], v[34:49]
	v_mfma_f32_32x32x16_bf16 v[50:65], v[130:133], v[138:141], v[50:65]
	ds_read_b128 v[130:133], v148 offset:18464
	ds_read_b128 v[134:137], v149 offset:55328
	ds_read_b128 v[138:141], v149 offset:59936
	s_waitcnt lgkmcnt(1)
	v_mfma_f32_32x32x16_bf16 v[2:17], v[130:133], v[134:137], v[2:17]
	s_waitcnt lgkmcnt(0)
	v_mfma_f32_32x32x16_bf16 v[18:33], v[130:133], v[138:141], v[18:33]
	ds_read_b128 v[130:133], v148 offset:23072
	s_waitcnt lgkmcnt(0)
	v_mfma_f32_32x32x16_bf16 v[34:49], v[130:133], v[134:137], v[34:49]
	v_mfma_f32_32x32x16_bf16 v[50:65], v[130:133], v[138:141], v[50:65]
	ds_read_b128 v[130:133], v148 offset:18496
	ds_read_b128 v[134:137], v149 offset:55360
	ds_read_b128 v[138:141], v149 offset:59968
	s_waitcnt lgkmcnt(1)
	v_mfma_f32_32x32x16_bf16 v[2:17], v[130:133], v[134:137], v[2:17]
	s_waitcnt lgkmcnt(0)
	v_mfma_f32_32x32x16_bf16 v[18:33], v[130:133], v[138:141], v[18:33]
	ds_read_b128 v[130:133], v148 offset:23104
	s_waitcnt lgkmcnt(0)
	v_mfma_f32_32x32x16_bf16 v[34:49], v[130:133], v[134:137], v[34:49]
	v_mfma_f32_32x32x16_bf16 v[50:65], v[130:133], v[138:141], v[50:65]
	ds_read_b128 v[130:133], v148 offset:18528
	ds_read_b128 v[134:137], v149 offset:55392
	ds_read_b128 v[138:141], v148 offset:23136
	ds_read_b128 v[208:211], v149 offset:60000
	s_waitcnt vmcnt(15)
	ds_write_b128 v174, v[66:69]
	s_waitcnt vmcnt(14)
	ds_write_b128 v174, v[74:77] offset:4608
	s_waitcnt vmcnt(13)
	ds_write_b128 v174, v[78:81] offset:9216
	s_waitcnt vmcnt(12)
	ds_write_b128 v174, v[82:85] offset:13824
	s_waitcnt vmcnt(11)
	ds_write_b128 v174, v[98:101] offset:36864
	s_waitcnt vmcnt(10)
	ds_write_b128 v174, v[118:121] offset:41472
	s_waitcnt vmcnt(9)
	ds_write_b128 v174, v[122:125] offset:46080
	s_waitcnt vmcnt(8)
	ds_write_b128 v174, v[126:129] offset:50688
	global_load_dwordx4 v[66:69], v[160:161], off offset:1792
	global_load_dwordx4 v[78:81], v[162:163], off offset:1792
	global_load_dwordx4 v[82:85], v[164:165], off offset:1792
	global_load_dwordx4 v[74:77], v[172:173], off offset:1792
	global_load_dwordx4 v[98:101], v[158:159], off offset:1792
	global_load_dwordx4 v[118:121], v[166:167], off offset:1792
	global_load_dwordx4 v[122:125], v[168:169], off offset:1792
	global_load_dwordx4 v[126:129], v[170:171], off offset:1792
	s_waitcnt lgkmcnt(0)
	s_barrier
	v_mfma_f32_32x32x16_bf16 v[2:17], v[130:133], v[134:137], v[2:17]
	v_mfma_f32_32x32x16_bf16 v[18:33], v[130:133], v[208:211], v[18:33]
	v_mfma_f32_32x32x16_bf16 v[34:49], v[138:141], v[134:137], v[34:49]
	v_mfma_f32_32x32x16_bf16 v[50:65], v[138:141], v[208:211], v[50:65]
	ds_read_b128 v[130:133], v148
	ds_read_b128 v[134:137], v149 offset:36864
	ds_read_b128 v[138:141], v149 offset:41472
	s_waitcnt lgkmcnt(1)
	v_mfma_f32_32x32x16_bf16 v[2:17], v[130:133], v[134:137], v[2:17]
	s_waitcnt lgkmcnt(0)
	v_mfma_f32_32x32x16_bf16 v[18:33], v[130:133], v[138:141], v[18:33]
	ds_read_b128 v[130:133], v148 offset:4608
	s_waitcnt lgkmcnt(0)
	v_mfma_f32_32x32x16_bf16 v[34:49], v[130:133], v[134:137], v[34:49]
	v_mfma_f32_32x32x16_bf16 v[50:65], v[130:133], v[138:141], v[50:65]
	ds_read_b128 v[130:133], v148 offset:32
	ds_read_b128 v[134:137], v149 offset:36896
	ds_read_b128 v[138:141], v149 offset:41504
	s_waitcnt lgkmcnt(1)
	v_mfma_f32_32x32x16_bf16 v[2:17], v[130:133], v[134:137], v[2:17]
	s_waitcnt lgkmcnt(0)
	v_mfma_f32_32x32x16_bf16 v[18:33], v[130:133], v[138:141], v[18:33]
	ds_read_b128 v[130:133], v148 offset:4640
	s_waitcnt lgkmcnt(0)
	v_mfma_f32_32x32x16_bf16 v[34:49], v[130:133], v[134:137], v[34:49]
	v_mfma_f32_32x32x16_bf16 v[50:65], v[130:133], v[138:141], v[50:65]
	ds_read_b128 v[130:133], v148 offset:64
	ds_read_b128 v[134:137], v149 offset:36928
	ds_read_b128 v[138:141], v149 offset:41536
	s_waitcnt lgkmcnt(1)
	v_mfma_f32_32x32x16_bf16 v[2:17], v[130:133], v[134:137], v[2:17]
	s_waitcnt lgkmcnt(0)
	v_mfma_f32_32x32x16_bf16 v[18:33], v[130:133], v[138:141], v[18:33]
	ds_read_b128 v[130:133], v148 offset:4672
	s_waitcnt lgkmcnt(0)
	v_mfma_f32_32x32x16_bf16 v[34:49], v[130:133], v[134:137], v[34:49]
	v_mfma_f32_32x32x16_bf16 v[50:65], v[130:133], v[138:141], v[50:65]
	ds_read_b128 v[130:133], v148 offset:96
	ds_read_b128 v[134:137], v149 offset:36960
	ds_read_b128 v[138:141], v148 offset:4704
	ds_read_b128 v[208:211], v149 offset:41568
	s_waitcnt vmcnt(15)
	ds_write_b128 v174, v[70:73] offset:18432
	s_waitcnt vmcnt(14)
	ds_write_b128 v174, v[86:89] offset:23040
	s_waitcnt vmcnt(13)
	ds_write_b128 v174, v[90:93] offset:27648
	s_waitcnt vmcnt(12)
	ds_write_b128 v174, v[94:97] offset:32256
	s_waitcnt vmcnt(11)
	ds_write_b128 v174, v[102:105] offset:55296
	s_waitcnt vmcnt(10)
	ds_write_b128 v174, v[106:109] offset:59904
	s_waitcnt vmcnt(9)
	ds_write_b128 v174, v[110:113] offset:64512
	s_waitcnt vmcnt(8)
	ds_write_b128 v175, v[114:117] offset:32256
	global_load_dwordx4 v[70:73], v[160:161], off offset:1920
	global_load_dwordx4 v[90:93], v[162:163], off offset:1920
	global_load_dwordx4 v[94:97], v[164:165], off offset:1920
	global_load_dwordx4 v[86:89], v[172:173], off offset:1920
	global_load_dwordx4 v[102:105], v[158:159], off offset:1920
	global_load_dwordx4 v[106:109], v[166:167], off offset:1920
	global_load_dwordx4 v[110:113], v[168:169], off offset:1920
	global_load_dwordx4 v[114:117], v[170:171], off offset:1920
	s_waitcnt lgkmcnt(0)
	s_barrier
	v_mfma_f32_32x32x16_bf16 v[2:17], v[130:133], v[134:137], v[2:17]
	v_mfma_f32_32x32x16_bf16 v[18:33], v[130:133], v[208:211], v[18:33]
	v_mfma_f32_32x32x16_bf16 v[34:49], v[138:141], v[134:137], v[34:49]
	v_mfma_f32_32x32x16_bf16 v[50:65], v[138:141], v[208:211], v[50:65]
	ds_read_b128 v[130:133], v148 offset:18432
	ds_read_b128 v[134:137], v149 offset:55296
	ds_read_b128 v[138:141], v149 offset:59904
	s_waitcnt lgkmcnt(1)
	v_mfma_f32_32x32x16_bf16 v[2:17], v[130:133], v[134:137], v[2:17]
	s_waitcnt lgkmcnt(0)
	v_mfma_f32_32x32x16_bf16 v[18:33], v[130:133], v[138:141], v[18:33]
	ds_read_b128 v[130:133], v148 offset:23040
	s_waitcnt lgkmcnt(0)
	v_mfma_f32_32x32x16_bf16 v[34:49], v[130:133], v[134:137], v[34:49]
	v_mfma_f32_32x32x16_bf16 v[50:65], v[130:133], v[138:141], v[50:65]
	ds_read_b128 v[130:133], v148 offset:18464
	ds_read_b128 v[134:137], v149 offset:55328
	ds_read_b128 v[138:141], v149 offset:59936
	s_waitcnt lgkmcnt(1)
	v_mfma_f32_32x32x16_bf16 v[2:17], v[130:133], v[134:137], v[2:17]
	s_waitcnt lgkmcnt(0)
	v_mfma_f32_32x32x16_bf16 v[18:33], v[130:133], v[138:141], v[18:33]
	ds_read_b128 v[130:133], v148 offset:23072
	s_waitcnt lgkmcnt(0)
	v_mfma_f32_32x32x16_bf16 v[34:49], v[130:133], v[134:137], v[34:49]
	v_mfma_f32_32x32x16_bf16 v[50:65], v[130:133], v[138:141], v[50:65]
	ds_read_b128 v[130:133], v148 offset:18496
	ds_read_b128 v[134:137], v149 offset:55360
	ds_read_b128 v[138:141], v149 offset:59968
	s_waitcnt lgkmcnt(1)
	v_mfma_f32_32x32x16_bf16 v[2:17], v[130:133], v[134:137], v[2:17]
	s_waitcnt lgkmcnt(0)
	v_mfma_f32_32x32x16_bf16 v[18:33], v[130:133], v[138:141], v[18:33]
	ds_read_b128 v[130:133], v148 offset:23104
	s_waitcnt lgkmcnt(0)
	v_mfma_f32_32x32x16_bf16 v[34:49], v[130:133], v[134:137], v[34:49]
	v_mfma_f32_32x32x16_bf16 v[50:65], v[130:133], v[138:141], v[50:65]
	ds_read_b128 v[130:133], v148 offset:18528
	ds_read_b128 v[134:137], v149 offset:55392
	ds_read_b128 v[138:141], v149 offset:60000
	s_waitcnt lgkmcnt(1)
	v_mfma_f32_32x32x16_bf16 v[2:17], v[130:133], v[134:137], v[2:17]
	s_waitcnt lgkmcnt(0)
	v_mfma_f32_32x32x16_bf16 v[18:33], v[130:133], v[138:141], v[18:33]
	ds_read_b128 v[130:133], v148 offset:23136
	s_waitcnt vmcnt(15)
	ds_write_b128 v174, v[66:69]
	s_waitcnt vmcnt(14)
	ds_write_b128 v174, v[78:81] offset:4608
	s_waitcnt vmcnt(13)
	ds_write_b128 v174, v[82:85] offset:9216
	s_waitcnt vmcnt(12)
	ds_write_b128 v174, v[74:77] offset:13824
	s_waitcnt vmcnt(11)
	ds_write_b128 v174, v[98:101] offset:36864
	s_waitcnt vmcnt(10)
	ds_write_b128 v174, v[118:121] offset:41472
	s_waitcnt vmcnt(9)
	ds_write_b128 v174, v[122:125] offset:46080
	s_waitcnt vmcnt(8)
	ds_write_b128 v174, v[126:129] offset:50688
	s_waitcnt lgkmcnt(0)
	s_barrier
	v_mfma_f32_32x32x16_bf16 v[34:49], v[130:133], v[134:137], v[34:49]
	v_mfma_f32_32x32x16_bf16 v[50:65], v[130:133], v[138:141], v[50:65]
	ds_read_b128 v[66:69], v148
	ds_read_b128 v[74:77], v149 offset:36864
	ds_read_b128 v[78:81], v149 offset:41472
	s_waitcnt lgkmcnt(1)
	v_mfma_f32_32x32x16_bf16 v[2:17], v[66:69], v[74:77], v[2:17]
	s_waitcnt lgkmcnt(0)
	v_mfma_f32_32x32x16_bf16 v[18:33], v[66:69], v[78:81], v[18:33]
	ds_read_b128 v[66:69], v148 offset:4608
	s_waitcnt lgkmcnt(0)
	v_mfma_f32_32x32x16_bf16 v[34:49], v[66:69], v[74:77], v[34:49]
	v_mfma_f32_32x32x16_bf16 v[50:65], v[66:69], v[78:81], v[50:65]
	ds_read_b128 v[66:69], v148 offset:32
	ds_read_b128 v[74:77], v149 offset:36896
	ds_read_b128 v[78:81], v149 offset:41504
	s_waitcnt lgkmcnt(1)
	v_mfma_f32_32x32x16_bf16 v[2:17], v[66:69], v[74:77], v[2:17]
	s_waitcnt lgkmcnt(0)
	v_mfma_f32_32x32x16_bf16 v[18:33], v[66:69], v[78:81], v[18:33]
	ds_read_b128 v[66:69], v148 offset:4640
	s_waitcnt lgkmcnt(0)
	v_mfma_f32_32x32x16_bf16 v[34:49], v[66:69], v[74:77], v[34:49]
	v_mfma_f32_32x32x16_bf16 v[50:65], v[66:69], v[78:81], v[50:65]
	ds_read_b128 v[66:69], v148 offset:64
	ds_read_b128 v[74:77], v149 offset:36928
	ds_read_b128 v[78:81], v149 offset:41536
	s_waitcnt lgkmcnt(1)
	v_mfma_f32_32x32x16_bf16 v[2:17], v[66:69], v[74:77], v[2:17]
	s_waitcnt lgkmcnt(0)
	v_mfma_f32_32x32x16_bf16 v[18:33], v[66:69], v[78:81], v[18:33]
	ds_read_b128 v[66:69], v148 offset:4672
	s_waitcnt lgkmcnt(0)
	v_mfma_f32_32x32x16_bf16 v[34:49], v[66:69], v[74:77], v[34:49]
	v_mfma_f32_32x32x16_bf16 v[50:65], v[66:69], v[78:81], v[50:65]
	ds_read_b128 v[66:69], v148 offset:96
	ds_read_b128 v[74:77], v149 offset:36960
	ds_read_b128 v[78:81], v149 offset:41568
	s_waitcnt lgkmcnt(1)
	v_mfma_f32_32x32x16_bf16 v[2:17], v[66:69], v[74:77], v[2:17]
	s_waitcnt lgkmcnt(0)
	v_mfma_f32_32x32x16_bf16 v[18:33], v[66:69], v[78:81], v[18:33]
	ds_read_b128 v[66:69], v148 offset:4704
	s_waitcnt vmcnt(7)
	ds_write_b128 v174, v[70:73] offset:18432
	s_waitcnt vmcnt(6)
	ds_write_b128 v174, v[90:93] offset:23040
	s_waitcnt vmcnt(5)
	ds_write_b128 v174, v[94:97] offset:27648
	s_waitcnt vmcnt(4)
	ds_write_b128 v174, v[86:89] offset:32256
	s_waitcnt vmcnt(3)
	ds_write_b128 v174, v[102:105] offset:55296
	s_waitcnt vmcnt(2)
	ds_write_b128 v174, v[106:109] offset:59904
	s_waitcnt vmcnt(1)
	ds_write_b128 v174, v[110:113] offset:64512
	s_waitcnt vmcnt(0)
	ds_write_b128 v175, v[114:117] offset:32256
	s_waitcnt lgkmcnt(0)
	s_barrier
	v_mfma_f32_32x32x16_bf16 v[34:49], v[66:69], v[74:77], v[34:49]
	v_mfma_f32_32x32x16_bf16 v[50:65], v[66:69], v[78:81], v[50:65]
	ds_read_b128 v[66:69], v148 offset:18432
	ds_read_b128 v[70:73], v149 offset:55296
	ds_read_b128 v[74:77], v149 offset:59904
	s_lshl_b32 s77, s76, 7
	s_cmp_eq_u32 s76, 5
	s_waitcnt lgkmcnt(1)
	v_mfma_f32_32x32x16_bf16 v[2:17], v[66:69], v[70:73], v[2:17]
	s_waitcnt lgkmcnt(0)
	v_mfma_f32_32x32x16_bf16 v[18:33], v[66:69], v[74:77], v[18:33]
	ds_read_b128 v[66:69], v148 offset:23040
	s_waitcnt lgkmcnt(0)
	v_mfma_f32_32x32x16_bf16 v[34:49], v[66:69], v[70:73], v[34:49]
	v_mfma_f32_32x32x16_bf16 v[50:65], v[66:69], v[74:77], v[50:65]
	ds_read_b128 v[66:69], v148 offset:18464
	ds_read_b128 v[70:73], v149 offset:55328
	ds_read_b128 v[74:77], v149 offset:59936
	s_waitcnt lgkmcnt(1)
	v_mfma_f32_32x32x16_bf16 v[2:17], v[66:69], v[70:73], v[2:17]
	s_waitcnt lgkmcnt(0)
	v_mfma_f32_32x32x16_bf16 v[18:33], v[66:69], v[74:77], v[18:33]
	ds_read_b128 v[66:69], v148 offset:23072
	s_waitcnt lgkmcnt(0)
	v_mfma_f32_32x32x16_bf16 v[34:49], v[66:69], v[70:73], v[34:49]
	v_mfma_f32_32x32x16_bf16 v[50:65], v[66:69], v[74:77], v[50:65]
	ds_read_b128 v[66:69], v148 offset:18496
	ds_read_b128 v[70:73], v149 offset:55360
	ds_read_b128 v[74:77], v149 offset:59968
	s_waitcnt lgkmcnt(1)
	v_mfma_f32_32x32x16_bf16 v[2:17], v[66:69], v[70:73], v[2:17]
	s_waitcnt lgkmcnt(0)
	v_mfma_f32_32x32x16_bf16 v[18:33], v[66:69], v[74:77], v[18:33]
	ds_read_b128 v[66:69], v148 offset:23104
	s_waitcnt lgkmcnt(0)
	v_mfma_f32_32x32x16_bf16 v[34:49], v[66:69], v[70:73], v[34:49]
	v_mfma_f32_32x32x16_bf16 v[50:65], v[66:69], v[74:77], v[50:65]
	ds_read_b128 v[66:69], v148 offset:18528
	ds_read_b128 v[70:73], v149 offset:55392
	ds_read_b128 v[74:77], v149 offset:60000
	s_waitcnt lgkmcnt(1)
	v_mfma_f32_32x32x16_bf16 v[2:17], v[66:69], v[70:73], v[2:17]
	s_waitcnt lgkmcnt(0)
	v_mfma_f32_32x32x16_bf16 v[18:33], v[66:69], v[74:77], v[18:33]
	ds_read_b128 v[66:69], v148 offset:23136
	s_waitcnt lgkmcnt(0)
	s_barrier
	v_mfma_f32_32x32x16_bf16 v[34:49], v[66:69], v[70:73], v[34:49]
	s_nop 7
	ds_write2_b32 v181, v2, v18 offset1:32
	v_mfma_f32_32x32x16_bf16 v[50:65], v[66:69], v[74:77], v[50:65]
	s_nop 11
	v_mov_b32_e32 v250, s26
	v_lshlrev_b32_e32 v250, 2, v250
	v_and_b32_e32 v246, 0x7f, v0
	v_lshlrev_b32_e32 v246, 2, v246
	v_add_u32_e32 v247, v250, v246
	global_load_dword v248, v247, s[16:17]
	v_add_u32_e32 v250, s16, v250
	v_subrev_u32_e32 v250, 0x10200, v250
	ds_write2_b32 v189, v34, v50 offset0:32 offset1:64
	ds_write2_b32 v181, v3, v19 offset0:129 offset1:161
	ds_write2_b32 v189, v35, v51 offset0:161 offset1:193
	ds_write2_b32 v190, v4, v20 offset0:2 offset1:34
	ds_write2_b32 v191, v36, v52 offset0:34 offset1:66
	ds_write2_b32 v190, v5, v21 offset0:131 offset1:163
	ds_write2_b32 v191, v37, v53 offset0:163 offset1:195
	ds_write2_b32 v192, v6, v22 offset0:8 offset1:40
	ds_write2_b32 v193, v38, v54 offset0:40 offset1:72
	ds_write2_b32 v192, v7, v23 offset0:137 offset1:169
	ds_write2_b32 v193, v39, v55 offset0:169 offset1:201
	ds_write2_b32 v194, v8, v24 offset0:10 offset1:42
	ds_write2_b32 v195, v40, v56 offset0:42 offset1:74
	ds_write2_b32 v194, v9, v25 offset0:139 offset1:171
	ds_write2_b32 v195, v41, v57 offset0:171 offset1:203
	ds_write2_b32 v196, v10, v26 offset0:16 offset1:48
	ds_write2_b32 v197, v42, v58 offset0:48 offset1:80
	ds_write2_b32 v196, v11, v27 offset0:145 offset1:177
	ds_write2_b32 v197, v43, v59 offset0:177 offset1:209
	ds_write2_b32 v198, v12, v28 offset0:18 offset1:50
	ds_write2_b32 v199, v44, v60 offset0:50 offset1:82
	ds_write2_b32 v198, v13, v29 offset0:147 offset1:179
	ds_write2_b32 v199, v45, v61 offset0:179 offset1:211
	ds_write2_b32 v200, v14, v30 offset0:24 offset1:56
	ds_write2_b32 v201, v46, v62 offset0:56 offset1:88
	ds_write2_b32 v200, v15, v31 offset0:153 offset1:185
	ds_write2_b32 v201, v47, v63 offset0:185 offset1:217
	ds_write2_b32 v202, v16, v32 offset0:26 offset1:58
	ds_write2_b32 v203, v48, v64 offset0:58 offset1:90
	ds_write2_b32 v202, v17, v33 offset0:155 offset1:187
	ds_write2_b32 v203, v49, v65 offset0:187 offset1:219
	s_waitcnt vmcnt(0)
	v_add_u32_e32 v246, 0x10200, v246
	ds_write_b32 v246, v248
	s_waitcnt lgkmcnt(0)
	s_barrier
	s_cbranch_scc1 .LBB0_79
	s_add_i32 s4, s77, 0xfffffa80
	s_cmpk_lt_u32 s4, 0x200
	s_cbranch_scc1 .LBB0_80
	s_add_i32 s4, s77, 0xfffff880
	s_cmpk_lt_u32 s4, 0x200
	s_cbranch_scc1 .LBB0_81
	s_add_i32 s4, s77, 0xfffff680
	s_mov_b64 s[24:25], -1
	s_cmpk_lt_u32 s4, 0x200
	s_mov_b64 s[22:23], 0
	s_cbranch_scc1 .LBB0_82
	s_cmp_lt_u32 s76, 23
	s_cbranch_scc1 .LBB0_83
	v_readlane_b32 s12, v252, 28
	s_movk_i32 s50, 0xb80
	s_mov_b64 s[90:91], 0x200
	s_mov_b64 s[42:43], -1
	v_readlane_b32 s13, v252, 29
	s_branch .LBB0_84

.LBB0_86:
	s_and_b32 s8, 0xffff, s44
	s_mul_hi_u32 s8, s8, 0x12f684c
	s_lshl_b32 s9, s3, 7
	s_lshl_b32 s8, s8, 13
	s_or_b32 s8, s8, s9
	s_lshl_b32 s9, s45, 7
	s_and_b32 s9, s9, 0x1c00
	s_or_b32 s8, s9, s8
	s_and_b32 s9, s51, 0xff
	s_mul_i32 s9, s9, 19
	s_bfe_u32 s9, s9, 0x70009
	s_mul_i32 s9, s9, 27
	s_sub_i32 s9, s51, s9
	s_and_b32 s51, s9, 0xff
	s_lshl_b32 s91, s51, 7
	s_cmp_lt_u32 s76, 4
	v_add_u32_e32 v142, s8, v180
	v_add_u32_e32 v25, s8, v185
	s_cselect_b64 s[58:59], -1, 0
	v_lshlrev_b32_e32 v18, 2, v25
	v_mov_b32_e32 v19, v143
	v_lshlrev_b32_e32 v20, 2, v142
	v_mov_b32_e32 v21, v143
	s_and_b64 vcc, exec, s[58:59]
	s_cbranch_vccnz .LBB0_139
	s_cmp_lg_u32 s76, 4
	s_cbranch_scc0 .LBB0_140
	s_add_i32 s9, s77, 0xfffffd00
	s_cmpk_lt_u32 s9, 0x200
	s_cselect_b64 s[58:59], -1, 0
	s_cmpk_gt_u32 s9, 0x1ff
	s_cbranch_scc0 .LBB0_141
	s_and_b64 s[24:25], s[38:39], s[24:25]
	s_andn2_b64 vcc, exec, s[24:25]
	s_mov_b64 s[24:25], -1
	s_cbranch_vccz .LBB0_104
	s_xor_b64 s[24:25], s[22:23], -1
	s_mov_b64 s[22:23], -1
	s_and_b64 vcc, exec, s[24:25]
	s_cbranch_vccz .LBB0_100
	v_add_u32_e32 v2, s26, v176
	v_mov_b32_e32 v3, v143
	v_lshl_add_u64 v[4:5], v[2:3], 2, s[16:17]
	v_sub_u32_e32 v249, v4, v250
	ds_read_b32 v4, v249
	s_movk_i32 s9, 0x53f
	s_waitcnt lgkmcnt(0)
	v_fmamk_f32 v4, v4, 0x3a800000, v188
	v_cmp_gt_f32_e32 vcc, s11, v4
	v_mul_f32_e32 v5, 0x4b800000, v4
	s_nop 0
	v_cndmask_b32_e32 v4, v4, v5, vcc
	v_rsq_f32_e32 v4, v4
	s_nop 0
	v_mul_f32_e32 v5, 0x45800000, v4
	v_cndmask_b32_e32 v24, v4, v5, vcc
	v_or_b32_e32 v4, s77, v177
	v_cmp_lt_i32_e32 vcc, s9, v4
	s_and_saveexec_b64 s[22:23], vcc
	s_xor_b64 s[22:23], exec, s[22:23]
	s_cbranch_execz .LBB0_95
	s_movk_i32 s9, 0x540
	v_cmp_eq_u32_e32 vcc, s9, v4
	s_and_saveexec_b64 s[24:25], vcc
	s_cbranch_execz .LBB0_94
	v_lshlrev_b64 v[2:3], 5, v[2:3]
	v_lshl_add_u64 v[6:7], s[64:65], 0, v[2:3]
	ds_read2_b32 v[2:3], v178 offset1:1
	ds_read2_b32 v[4:5], v178 offset0:2 offset1:3
	s_waitcnt lgkmcnt(1)
	v_pk_mul_f32 v[2:3], v[24:25], v[2:3] op_sel_hi:[0,1]
	s_waitcnt lgkmcnt(0)
	v_pk_mul_f32 v[4:5], v[24:25], v[4:5] op_sel_hi:[0,1]
	global_store_dwordx4 v[6:7], v[2:5], off
	ds_read2_b32 v[2:3], v178 offset0:4 offset1:5
	ds_read2_b32 v[4:5], v178 offset0:6 offset1:7
	s_waitcnt lgkmcnt(1)
	v_pk_mul_f32 v[2:3], v[24:25], v[2:3] op_sel_hi:[0,1]
	s_waitcnt lgkmcnt(0)
	v_pk_mul_f32 v[4:5], v[24:25], v[4:5] op_sel_hi:[0,1]
	global_store_dwordx4 v[6:7], v[2:5], off offset:16

.LBB0_102:
	s_nop 0
	v_lshl_add_u64 v[2:3], v[6:7], 0, s[22:23]
	v_sub_u32_e32 v249, v2, v250
	ds_read_b32 v2, v249
	s_waitcnt lgkmcnt(0)
	v_fmamk_f32 v2, v2, 0x3a800000, v188
	v_cmp_gt_f32_e32 vcc, s11, v2
	v_mul_f32_e32 v3, 0x4b800000, v2
	s_nop 0
	v_cndmask_b32_e32 v2, v2, v3, vcc
	v_rsq_f32_e32 v2, v2
	s_nop 0
	v_mul_f32_e32 v3, 0x45800000, v2
	v_cndmask_b32_e32 v4, v2, v3, vcc
	ds_read2_b32 v[2:3], v29 offset0:2 offset1:3
	s_waitcnt lgkmcnt(0)
	v_mul_f32_e32 v5, v3, v4
	v_mul_f32_e32 v30, v2, v4
	ds_read2_b32 v[2:3], v29 offset1:1
	v_mul_f32_e32 v5, 0xbfb8aa3b, v5
	v_exp_f32_e32 v5, v5
	s_waitcnt lgkmcnt(0)
	v_mul_f32_e32 v2, v2, v4
	v_mul_f32_e32 v2, 0xbfb8aa3b, v2
	v_exp_f32_e32 v2, v2
	v_mul_f32_e32 v3, v3, v4
	v_mul_f32_e32 v3, 0xbfb8aa3b, v3
	v_exp_f32_e32 v3, v3
	v_add_f32_e32 v2, 1.0, v2
	v_div_scale_f32 v4, s[4:5], v2, v2, 1.0
	v_rcp_f32_e32 v31, v4
	v_add_f32_e32 v3, 1.0, v3
	v_add_f32_e32 v5, 1.0, v5
	v_fma_f32 v32, -v4, v31, 1.0
	v_fmac_f32_e32 v31, v32, v31
	v_div_scale_f32 v32, vcc, 1.0, v2, 1.0
	v_mul_f32_e32 v33, v32, v31
	v_fma_f32 v34, -v4, v33, v32
	v_fmac_f32_e32 v33, v34, v31
	v_fma_f32 v4, -v4, v33, v32
	v_div_fmas_f32 v4, v4, v31, v33
	v_div_fixup_f32 v2, v4, v2, 1.0
	v_fma_f32 v2, v24, v2, v16
	v_cmp_gt_f32_e32 vcc, s11, v2
	s_nop 1
	v_cndmask_b32_e64 v4, 0, 32, vcc
	v_ldexp_f32 v2, v2, v4
	v_log_f32_e32 v2, v2
	s_nop 0
	v_mul_f32_e32 v4, 0x3f317217, v2
	v_fma_f32 v4, v2, s21, -v4
	v_fmac_f32_e32 v4, 0x3377d1cf, v2
	v_fmac_f32_e32 v4, 0x3f317217, v2
	v_cmp_lt_f32_e64 s[4:5], |v2|, s96
	s_nop 1
	v_cndmask_b32_e64 v2, v2, v4, s[4:5]
	v_cndmask_b32_e32 v4, 0, v205, vcc
	v_sub_f32_e32 v2, v2, v4
	v_div_scale_f32 v4, s[4:5], v3, v3, 1.0
	v_rcp_f32_e32 v31, v4
	s_nop 0
	v_fma_f32 v32, -v4, v31, 1.0
	v_fmac_f32_e32 v31, v32, v31
	v_div_scale_f32 v32, vcc, 1.0, v3, 1.0
	v_mul_f32_e32 v33, v32, v31
	v_fma_f32 v34, -v4, v33, v32
	v_fmac_f32_e32 v33, v34, v31
	v_fma_f32 v4, -v4, v33, v32
	v_div_fmas_f32 v4, v4, v31, v33
	v_div_fixup_f32 v3, v4, v3, 1.0
	v_fma_f32 v3, v26, v3, v17
	v_cmp_gt_f32_e32 vcc, s11, v3
	s_nop 1
	v_cndmask_b32_e64 v4, 0, 32, vcc
	v_ldexp_f32 v3, v3, v4
	v_log_f32_e32 v3, v3
	s_nop 0
	v_mul_f32_e32 v4, 0x3f317217, v3
	v_fma_f32 v4, v3, s21, -v4
	v_fmac_f32_e32 v4, 0x3377d1cf, v3
	v_fmac_f32_e32 v4, 0x3f317217, v3
	v_cmp_lt_f32_e64 s[4:5], |v3|, s96
	s_nop 1
	v_cndmask_b32_e64 v3, v3, v4, s[4:5]
	v_cndmask_b32_e32 v4, 0, v205, vcc
	v_sub_f32_e32 v3, v3, v4
	v_mul_f32_e32 v4, 0xbfb8aa3b, v30
	v_exp_f32_e32 v4, v4
	s_nop 0
	v_add_f32_e32 v4, 1.0, v4
	v_div_scale_f32 v30, s[4:5], v4, v4, 1.0
	v_rcp_f32_e32 v31, v30
	s_nop 0
	v_fma_f32 v32, -v30, v31, 1.0
	v_fmac_f32_e32 v31, v32, v31
	v_div_scale_f32 v32, vcc, 1.0, v4, 1.0
	v_mul_f32_e32 v33, v32, v31
	v_fma_f32 v34, -v30, v33, v32
	v_fmac_f32_e32 v33, v34, v31
	v_fma_f32 v30, -v30, v33, v32
	v_div_fmas_f32 v30, v30, v31, v33
	v_div_fixup_f32 v4, v30, v4, 1.0
	v_fma_f32 v4, v27, v4, v22
	v_cmp_gt_f32_e32 vcc, s11, v4
	s_nop 1
	v_cndmask_b32_e64 v30, 0, 32, vcc
	v_ldexp_f32 v4, v4, v30
	v_log_f32_e32 v4, v4
	s_nop 0
	v_mul_f32_e32 v30, 0x3f317217, v4
	v_fma_f32 v30, v4, s21, -v30
	v_fmac_f32_e32 v30, 0x3377d1cf, v4
	v_fmac_f32_e32 v30, 0x3f317217, v4
	v_cmp_lt_f32_e64 s[4:5], |v4|, s96
	s_nop 1
	v_cndmask_b32_e64 v4, v4, v30, s[4:5]
	v_cndmask_b32_e32 v30, 0, v205, vcc
	v_sub_f32_e32 v4, v4, v30
	v_div_scale_f32 v30, s[4:5], v5, v5, 1.0
	v_rcp_f32_e32 v31, v30
	s_nop 0
	v_fma_f32 v32, -v30, v31, 1.0
	v_fmac_f32_e32 v31, v32, v31
	v_div_scale_f32 v32, vcc, 1.0, v5, 1.0
	v_mul_f32_e32 v33, v32, v31
	v_fma_f32 v34, -v30, v33, v32
	v_fmac_f32_e32 v33, v34, v31
	v_fma_f32 v30, -v30, v33, v32
	v_div_fmas_f32 v30, v30, v31, v33
	v_div_fixup_f32 v5, v30, v5, 1.0
	v_fma_f32 v5, v28, v5, v23
	v_cmp_gt_f32_e32 vcc, s11, v5
	s_nop 1
	v_cndmask_b32_e64 v30, 0, 32, vcc
	v_ldexp_f32 v5, v5, v30
	v_log_f32_e32 v5, v5
	s_nop 0
	v_mul_f32_e32 v30, 0x3f317217, v5
	v_fma_f32 v30, v5, s21, -v30
	v_fmac_f32_e32 v30, 0x3377d1cf, v5
	v_fmac_f32_e32 v30, 0x3f317217, v5
	v_cmp_lt_f32_e64 s[4:5], |v5|, s96
	s_nop 1
	v_cndmask_b32_e64 v5, v5, v30, s[4:5]
	v_cndmask_b32_e32 v30, 0, v205, vcc
	v_sub_f32_e32 v5, v5, v30
	v_lshl_add_u64 v[30:31], v[10:11], 0, v[12:13]
	global_store_dwordx4 v[30:31], v[2:5], off
	s_nop 1
	v_lshl_add_u64 v[2:3], v[8:9], 0, s[22:23]
	v_sub_u32_e32 v249, v2, v250
	ds_read_b32 v2, v249
	v_add_u32_e32 v5, 0x1020, v29
	s_add_u32 s22, s22, 64
	s_addc_u32 s23, s23, 0
	s_cmpk_eq_i32 s22, 0x200
	s_waitcnt lgkmcnt(0)
	v_fmamk_f32 v2, v2, 0x3a800000, v188
	v_cmp_gt_f32_e32 vcc, s11, v2
	v_mul_f32_e32 v3, 0x4b800000, v2
	s_nop 0
	v_cndmask_b32_e32 v2, v2, v3, vcc
	v_rsq_f32_e32 v2, v2
	s_nop 0
	v_mul_f32_e32 v3, 0x45800000, v2
	v_cndmask_b32_e32 v4, v2, v3, vcc
	v_add_u32_e32 v2, 0x1028, v29
	ds_read2_b32 v[2:3], v2 offset1:1
	v_add_u32_e32 v29, 0x2040, v29
	s_waitcnt lgkmcnt(0)
	v_mul_f32_e32 v30, v3, v4
	v_mul_f32_e32 v31, v2, v4
	ds_read2_b32 v[2:3], v5 offset1:1
	s_waitcnt lgkmcnt(0)
	v_mul_f32_e32 v2, v2, v4
	v_mul_f32_e32 v2, 0xbfb8aa3b, v2
	v_exp_f32_e32 v2, v2
	v_mul_f32_e32 v3, v3, v4
	v_mul_f32_e32 v3, 0xbfb8aa3b, v3
	v_exp_f32_e32 v3, v3
	v_add_f32_e32 v2, 1.0, v2
	v_div_scale_f32 v4, s[4:5], v2, v2, 1.0
	v_rcp_f32_e32 v5, v4
	v_add_f32_e32 v3, 1.0, v3
	v_fma_f32 v32, -v4, v5, 1.0
	v_fmac_f32_e32 v5, v32, v5
	v_div_scale_f32 v32, vcc, 1.0, v2, 1.0
	v_mul_f32_e32 v33, v32, v5
	v_fma_f32 v34, -v4, v33, v32
	v_fmac_f32_e32 v33, v34, v5
	v_fma_f32 v4, -v4, v33, v32
	v_div_fmas_f32 v4, v4, v5, v33
	v_div_fixup_f32 v2, v4, v2, 1.0
	v_fma_f32 v2, v24, v2, v16
	v_cmp_gt_f32_e32 vcc, s11, v2
	s_nop 1
	v_cndmask_b32_e64 v4, 0, 32, vcc
	v_ldexp_f32 v2, v2, v4
	v_log_f32_e32 v2, v2
	s_nop 0
	v_mul_f32_e32 v4, 0x3f317217, v2
	v_fma_f32 v4, v2, s21, -v4
	v_fmac_f32_e32 v4, 0x3377d1cf, v2
	v_fmac_f32_e32 v4, 0x3f317217, v2
	v_cmp_lt_f32_e64 s[4:5], |v2|, s96
	s_nop 1
	v_cndmask_b32_e64 v2, v2, v4, s[4:5]
	v_cndmask_b32_e32 v4, 0, v205, vcc
	v_sub_f32_e32 v2, v2, v4
	v_div_scale_f32 v4, s[4:5], v3, v3, 1.0
	v_rcp_f32_e32 v5, v4
	s_nop 0
	v_fma_f32 v32, -v4, v5, 1.0
	v_fmac_f32_e32 v5, v32, v5
	v_div_scale_f32 v32, vcc, 1.0, v3, 1.0
	v_mul_f32_e32 v33, v32, v5
	v_fma_f32 v34, -v4, v33, v32
	v_fmac_f32_e32 v33, v34, v5
	v_fma_f32 v4, -v4, v33, v32
	v_div_fmas_f32 v4, v4, v5, v33
	v_div_fixup_f32 v3, v4, v3, 1.0
	v_fma_f32 v3, v26, v3, v17
	v_cmp_gt_f32_e32 vcc, s11, v3
	s_nop 1
	v_cndmask_b32_e64 v4, 0, 32, vcc
	v_ldexp_f32 v3, v3, v4
	v_log_f32_e32 v3, v3
	s_nop 0
	v_mul_f32_e32 v4, 0x3f317217, v3
	v_fma_f32 v4, v3, s21, -v4
	v_fmac_f32_e32 v4, 0x3377d1cf, v3
	v_fmac_f32_e32 v4, 0x3f317217, v3
	v_cmp_lt_f32_e64 s[4:5], |v3|, s96
	s_nop 1
	v_cndmask_b32_e64 v3, v3, v4, s[4:5]
	v_cndmask_b32_e32 v4, 0, v205, vcc
	v_sub_f32_e32 v3, v3, v4
	v_mul_f32_e32 v4, 0xbfb8aa3b, v31
	v_exp_f32_e32 v4, v4
	s_nop 0
	v_add_f32_e32 v4, 1.0, v4
	v_div_scale_f32 v5, s[4:5], v4, v4, 1.0
	v_rcp_f32_e32 v31, v5
	s_nop 0
	v_fma_f32 v32, -v5, v31, 1.0
	v_fmac_f32_e32 v31, v32, v31
	v_div_scale_f32 v32, vcc, 1.0, v4, 1.0
	v_mul_f32_e32 v33, v32, v31
	v_fma_f32 v34, -v5, v33, v32
	v_fmac_f32_e32 v33, v34, v31
	v_fma_f32 v5, -v5, v33, v32
	v_div_fmas_f32 v5, v5, v31, v33
	v_div_fixup_f32 v4, v5, v4, 1.0
	v_fma_f32 v4, v27, v4, v22
	v_cmp_gt_f32_e32 vcc, s11, v4
	s_nop 1
	v_cndmask_b32_e64 v5, 0, 32, vcc
	v_ldexp_f32 v4, v4, v5
	v_log_f32_e32 v4, v4
	s_nop 0
	v_mul_f32_e32 v5, 0x3f317217, v4
	v_fma_f32 v5, v4, s21, -v5
	v_fmac_f32_e32 v5, 0x3377d1cf, v4
	v_fmac_f32_e32 v5, 0x3f317217, v4
	v_cmp_lt_f32_e64 s[4:5], |v4|, s96
	s_nop 1
	v_cndmask_b32_e64 v4, v4, v5, s[4:5]
	v_cndmask_b32_e32 v5, 0, v205, vcc
	v_sub_f32_e32 v4, v4, v5
	v_mul_f32_e32 v5, 0xbfb8aa3b, v30
	v_exp_f32_e32 v5, v5
	s_nop 0
	v_add_f32_e32 v5, 1.0, v5
	v_div_scale_f32 v30, s[4:5], v5, v5, 1.0
	v_rcp_f32_e32 v31, v30
	s_nop 0
	v_fma_f32 v32, -v30, v31, 1.0
	v_fmac_f32_e32 v31, v32, v31
	v_div_scale_f32 v32, vcc, 1.0, v5, 1.0
	v_mul_f32_e32 v33, v32, v31
	v_fma_f32 v34, -v30, v33, v32
	v_fmac_f32_e32 v33, v34, v31
	v_fma_f32 v30, -v30, v33, v32
	v_div_fmas_f32 v30, v30, v31, v33
	v_div_fixup_f32 v5, v30, v5, 1.0
	v_fma_f32 v5, v28, v5, v23
	v_cmp_gt_f32_e32 vcc, s11, v5
	s_nop 1
	v_cndmask_b32_e64 v30, 0, 32, vcc
	v_ldexp_f32 v5, v5, v30
	v_log_f32_e32 v5, v5
	s_nop 0
	v_mul_f32_e32 v30, 0x3f317217, v5
	v_fma_f32 v30, v5, s21, -v30
	v_fmac_f32_e32 v30, 0x3377d1cf, v5
	v_fmac_f32_e32 v30, 0x3f317217, v5
	v_cmp_lt_f32_e64 s[4:5], |v5|, s96
	s_nop 1
	v_cndmask_b32_e64 v5, v5, v30, s[4:5]
	v_cndmask_b32_e32 v30, 0, v205, vcc
	v_sub_f32_e32 v5, v5, v30
	v_lshl_add_u64 v[30:31], v[14:15], 0, v[12:13]
	v_lshl_add_u64 v[12:13], v[12:13], 0, s[26:27]
	global_store_dwordx4 v[30:31], v[2:5], off
	s_cbranch_scc0 .LBB0_102

.LBB0_107:
	v_lshl_add_u64 v[14:15], v[4:5], 0, s[12:13]
	v_sub_u32_e32 v249, v14, v250
	ds_read_b32 v13, v249
	v_cndmask_b32_e64 v15, 0, 1, s[42:43]
	v_cmp_ne_u32_e64 s[4:5], 1, v15
	s_waitcnt lgkmcnt(0)
	v_fmamk_f32 v13, v13, 0x3a800000, v188
	v_cmp_gt_f32_e32 vcc, s11, v13
	v_mul_f32_e32 v14, 0x4b800000, v13
	s_nop 0
	v_cndmask_b32_e32 v13, v13, v14, vcc
	v_rsq_f32_e32 v13, v13
	s_nop 0
	v_mul_f32_e32 v14, 0x45800000, v13
	v_cndmask_b32_e32 v14, v13, v14, vcc
	ds_read_b32 v13, v12
	s_andn2_b64 vcc, exec, s[42:43]
	s_waitcnt lgkmcnt(0)
	v_mul_f32_e32 v13, v13, v14
	s_cbranch_vccz .LBB0_124
	ds_read_b32 v15, v12 offset:4
	s_and_b64 vcc, exec, s[4:5]
	s_waitcnt lgkmcnt(0)
	v_mul_f32_e32 v15, v14, v15
	s_cbranch_vccz .LBB0_125

.LBB0_116:
	v_and_b32_sdwa v26, v16, v204 dst_sel:DWORD dst_unused:UNUSED_PAD src0_sel:WORD_1 src1_sel:DWORD
	v_and_b32_sdwa v27, v13, v204 dst_sel:DWORD dst_unused:UNUSED_PAD src0_sel:WORD_1 src1_sel:DWORD
	v_add3_u32 v16, v16, v26, s20
	v_and_b32_sdwa v26, v17, v204 dst_sel:DWORD dst_unused:UNUSED_PAD src0_sel:WORD_1 src1_sel:DWORD
	v_add3_u32 v13, v13, v27, s20
	v_and_b32_sdwa v27, v15, v204 dst_sel:DWORD dst_unused:UNUSED_PAD src0_sel:WORD_1 src1_sel:DWORD
	v_add3_u32 v17, v17, v26, s20
	v_add3_u32 v15, v15, v27, s20
	v_and_b32_e32 v17, 0xffff0000, v17
	v_and_b32_e32 v15, 0xffff0000, v15
	v_or_b32_sdwa v27, v17, v16 dst_sel:DWORD dst_unused:UNUSED_PAD src0_sel:DWORD src1_sel:WORD_1
	v_and_b32_sdwa v16, v14, v204 dst_sel:DWORD dst_unused:UNUSED_PAD src0_sel:WORD_1 src1_sel:DWORD
	v_and_b32_sdwa v17, v23, v204 dst_sel:DWORD dst_unused:UNUSED_PAD src0_sel:WORD_1 src1_sel:DWORD
	v_or_b32_sdwa v26, v15, v13 dst_sel:DWORD dst_unused:UNUSED_PAD src0_sel:DWORD src1_sel:WORD_1
	v_and_b32_sdwa v13, v24, v204 dst_sel:DWORD dst_unused:UNUSED_PAD src0_sel:WORD_1 src1_sel:DWORD
	v_and_b32_sdwa v15, v22, v204 dst_sel:DWORD dst_unused:UNUSED_PAD src0_sel:WORD_1 src1_sel:DWORD
	v_add3_u32 v14, v14, v16, s20
	v_add3_u32 v16, v23, v17, s20
	v_add3_u32 v15, v22, v15, s20
	v_add3_u32 v13, v24, v13, s20
	v_and_b32_e32 v14, 0xffff0000, v14
	v_and_b32_e32 v16, 0xffff0000, v16
	v_lshl_add_u64 v[30:31], v[6:7], 0, v[8:9]
	v_or_b32_sdwa v29, v14, v13 dst_sel:DWORD dst_unused:UNUSED_PAD src0_sel:DWORD src1_sel:WORD_1
	v_or_b32_sdwa v28, v16, v15 dst_sel:DWORD dst_unused:UNUSED_PAD src0_sel:DWORD src1_sel:WORD_1
	global_store_dwordx4 v[30:31], v[26:29], off
	v_lshl_add_u64 v[14:15], v[2:3], 0, s[12:13]
	v_sub_u32_e32 v249, v14, v250
	ds_read_b32 v13, v249
	s_waitcnt lgkmcnt(0)
	v_fmamk_f32 v13, v13, 0x3a800000, v188
	v_mul_f32_e32 v14, 0x4b800000, v13
	v_cmp_gt_f32_e32 vcc, s11, v13
	s_nop 1
	v_cndmask_b32_e32 v13, v13, v14, vcc
	v_rsq_f32_e32 v13, v13
	ds_read_b32 v14, v12 offset:8256
	v_mul_f32_e32 v15, 0x45800000, v13
	v_cndmask_b32_e32 v15, v13, v15, vcc
	s_and_b64 vcc, exec, s[4:5]
	s_waitcnt lgkmcnt(0)
	v_mul_f32_e32 v13, v14, v15
	s_cbranch_vccz .LBB0_131
	ds_read_b32 v14, v12 offset:8260
	s_and_b64 vcc, exec, s[4:5]
	s_waitcnt lgkmcnt(0)
	v_mul_f32_e32 v14, v15, v14
	s_cbranch_vccz .LBB0_132

.LBB0_144:
	s_nop 0
	v_lshl_add_u64 v[2:3], s[82:83], 0, v[10:11]
	v_sub_u32_e32 v249, v2, v250
	ds_read_b32 v2, v249
	v_add_u32_e32 v42, s8, v187
	ds_read2_b32 v[4:5], v42 offset1:1
	v_add_u32_e32 v41, s8, v186
	v_mbcnt_hi_u32_b32 v43, -1, v206
	s_waitcnt lgkmcnt(0)
	v_fmamk_f32 v2, v2, 0x3a800000, v188
	v_cmp_gt_f32_e32 vcc, s11, v2
	v_mul_f32_e32 v3, 0x4b800000, v2
	s_nop 0
	v_cndmask_b32_e32 v2, v2, v3, vcc
	v_rsq_f32_e32 v2, v2
	s_nop 0
	v_mul_f32_e32 v3, 0x45800000, v2
	v_cndmask_b32_e32 v2, v2, v3, vcc
	s_waitcnt lgkmcnt(0)
	v_pk_mul_f32 v[34:35], v[4:5], v[2:3] op_sel_hi:[1,0]
	ds_read2_b32 v[4:5], v41 offset1:1
	s_andn2_b64 vcc, exec, s[22:23]
	s_waitcnt lgkmcnt(0)
	v_pk_mul_f32 v[30:31], v[4:5], v[2:3] op_sel_hi:[1,0]
	ds_read2_b32 v[4:5], v42 offset0:2 offset1:3
	s_waitcnt lgkmcnt(0)
	v_pk_mul_f32 v[38:39], v[4:5], v[2:3] op_sel_hi:[1,0]
	ds_read2_b32 v[4:5], v41 offset0:2 offset1:3
	s_waitcnt lgkmcnt(0)
	v_pk_mul_f32 v[32:33], v[4:5], v[2:3] op_sel_hi:[1,0]
	ds_read2_b32 v[4:5], v42 offset0:4 offset1:5
	s_waitcnt lgkmcnt(0)
	v_pk_mul_f32 v[28:29], v[2:3], v[4:5] op_sel_hi:[0,1]
	ds_read2_b32 v[4:5], v41 offset0:4 offset1:5
	s_waitcnt lgkmcnt(0)
	v_pk_mul_f32 v[24:25], v[2:3], v[4:5] op_sel_hi:[0,1]
	ds_read2_b32 v[4:5], v42 offset0:6 offset1:7
	s_waitcnt lgkmcnt(0)
	v_pk_mul_f32 v[36:37], v[2:3], v[4:5] op_sel_hi:[0,1]
	ds_read2_b32 v[4:5], v41 offset0:6 offset1:7
	s_waitcnt lgkmcnt(0)
	v_pk_mul_f32 v[26:27], v[2:3], v[4:5] op_sel_hi:[0,1]
	v_cndmask_b32_e64 v2, 0, 1, s[22:23]
	v_cmp_ne_u32_e64 s[4:5], 1, v2
	s_cbranch_vccnz .LBB0_146
	v_pk_mul_f32 v[2:3], v[34:35], v[34:35]
	v_pk_mul_f32 v[4:5], v[38:39], v[38:39]
	v_add_f32_e32 v2, v2, v3
	v_add_f32_e32 v2, v4, v2
	v_pk_mul_f32 v[44:45], v[28:29], v[28:29]
	v_add_f32_e32 v2, v5, v2
	v_and_b32_e32 v4, 64, v43
	v_add_f32_e32 v2, v44, v2
	v_xor_b32_e32 v3, 1, v43
	v_add_u32_e32 v4, 64, v4
	v_pk_mul_f32 v[46:47], v[36:37], v[36:37]
	v_add_f32_e32 v2, v45, v2
	v_cmp_lt_i32_e32 vcc, v3, v4
	v_add_f32_e32 v2, v2, v46
	v_add_f32_e32 v2, v2, v47
	v_cndmask_b32_e32 v3, v43, v3, vcc
	v_lshlrev_b32_e32 v3, 2, v3
	ds_bpermute_b32 v3, v3, v2
	s_waitcnt lgkmcnt(0)
	v_add_f32_e32 v2, v2, v3
	v_xor_b32_e32 v3, 2, v43
	v_cmp_lt_i32_e32 vcc, v3, v4
	s_nop 1
	v_cndmask_b32_e32 v3, v43, v3, vcc
	v_lshlrev_b32_e32 v3, 2, v3
	ds_bpermute_b32 v3, v3, v2
	s_waitcnt lgkmcnt(0)
	v_add_f32_e32 v2, v2, v3
	v_xor_b32_e32 v3, 4, v43
	v_cmp_lt_i32_e32 vcc, v3, v4
	s_nop 1
	v_cndmask_b32_e32 v3, v43, v3, vcc
	v_lshlrev_b32_e32 v3, 2, v3
	ds_bpermute_b32 v3, v3, v2
	s_waitcnt lgkmcnt(0)
	v_add_f32_e32 v2, v2, v3
	v_fmamk_f32 v2, v2, 0x3c800000, v188
	v_cmp_gt_f32_e32 vcc, s11, v2
	v_mul_f32_e32 v3, 0x4b800000, v2
	s_nop 0
	v_cndmask_b32_e32 v2, v2, v3, vcc
	v_rsq_f32_e32 v2, v2
	s_nop 0
	v_mul_f32_e32 v3, 0x45800000, v2
	v_cndmask_b32_e32 v40, v2, v3, vcc
	global_load_dwordx4 v[2:5], v[14:15], off offset:16
	global_load_dwordx4 v[44:47], v[14:15], off
	global_load_dwordx4 v[48:51], v[16:17], off offset:16
	global_load_dwordx4 v[52:55], v[16:17], off
	s_waitcnt vmcnt(3)
	v_pk_mul_f32 v[2:3], v[40:41], v[2:3] op_sel_hi:[0,1]
	s_waitcnt vmcnt(2)
	v_pk_mul_f32 v[44:45], v[44:45], v[40:41] op_sel_hi:[1,0]
	v_pk_mul_f32 v[28:29], v[28:29], v[2:3]
	v_pk_mul_f32 v[34:35], v[34:35], v[44:45]
	s_waitcnt vmcnt(0)
	v_pk_mul_f32 v[44:45], v[52:53], v[40:41] op_sel_hi:[1,0]
	v_pk_mul_f32 v[2:3], v[40:41], v[48:49] op_sel_hi:[0,1]
	v_pk_mul_f32 v[30:31], v[30:31], v[44:45]
	v_pk_mul_f32 v[44:45], v[46:47], v[40:41] op_sel_hi:[1,0]
	v_pk_mul_f32 v[24:25], v[24:25], v[2:3]
	v_pk_mul_f32 v[2:3], v[40:41], v[4:5] op_sel_hi:[0,1]
	v_pk_mul_f32 v[38:39], v[38:39], v[44:45]
	v_pk_mul_f32 v[44:45], v[54:55], v[40:41] op_sel_hi:[1,0]
	v_pk_mul_f32 v[36:37], v[36:37], v[2:3]
	v_pk_mul_f32 v[2:3], v[40:41], v[50:51] op_sel_hi:[0,1]
	v_pk_mul_f32 v[32:33], v[32:33], v[44:45]
	v_pk_mul_f32 v[26:27], v[26:27], v[2:3]
.LBB0_146:
	v_mov_b32_e32 v2, v29
	v_mov_b32_e32 v29, v36
	v_mov_b32_e32 v3, v37
	v_lshl_add_u64 v[36:37], s[82:83], 0, v[12:13]
	v_lshl_add_u64 v[52:53], v[36:37], 0, s[34:35]
	v_add_co_u32_e32 v36, vcc, s97, v36
	v_mov_b32_e32 v4, v35
	s_nop 0
	v_addc_co_u32_e32 v37, vcc, 0, v37, vcc
	v_mov_b32_e32 v35, v38
	v_mov_b32_e32 v5, v39
	global_load_dwordx4 v[36:39], v[36:37], off
	s_nop 0
	global_load_dwordx4 v[44:47], v[52:53], off offset:48
	global_load_dwordx4 v[48:51], v[52:53], off offset:32
	s_nop 0
	global_load_dwordx4 v[52:55], v[52:53], off offset:16
	v_cndmask_b32_e64 v60, v30, -v30, s[6:7]
	v_cndmask_b32_e64 v61, v32, -v32, s[6:7]
	v_cndmask_b32_e64 v30, v31, -v31, s[6:7]
	v_cndmask_b32_e64 v31, v33, -v33, s[6:7]
	v_lshl_add_u64 v[56:57], v[18:19], 0, v[20:21]
	s_waitcnt vmcnt(3)
	v_mov_b32_e32 v58, v36
	s_waitcnt vmcnt(0)
	v_mov_b32_e32 v59, v52
	v_mov_b32_e32 v52, v37
	v_pk_mul_f32 v[36:37], v[60:61], v[52:53]
	s_nop 0
	v_pk_fma_f32 v[34:35], v[34:35], v[58:59], v[36:37]
	v_mov_b32_e32 v37, v54
	v_mov_b32_e32 v54, v39
	v_mov_b32_e32 v36, v38
	v_pk_mul_f32 v[30:31], v[30:31], v[54:55]
	v_pk_mul_f32 v[34:35], s[12:13], v[34:35]
	v_pk_fma_f32 v[4:5], v[4:5], v[36:37], v[30:31]
	v_and_b32_sdwa v31, v34, v204 dst_sel:DWORD dst_unused:UNUSED_PAD src0_sel:WORD_1 src1_sel:DWORD
	v_pk_mul_f32 v[4:5], s[12:13], v[4:5]
	v_add3_u32 v32, v34, v31, s20
	v_and_b32_sdwa v31, v5, v204 dst_sel:DWORD dst_unused:UNUSED_PAD src0_sel:WORD_1 src1_sel:DWORD
	v_and_b32_sdwa v33, v4, v204 dst_sel:DWORD dst_unused:UNUSED_PAD src0_sel:WORD_1 src1_sel:DWORD
	v_and_b32_sdwa v30, v35, v204 dst_sel:DWORD dst_unused:UNUSED_PAD src0_sel:WORD_1 src1_sel:DWORD
	v_add3_u32 v5, v5, v31, s20
	v_add3_u32 v4, v4, v33, s20
	v_add3_u32 v30, v35, v30, s20
	v_and_b32_e32 v5, 0xffff0000, v5
	v_and_b32_e32 v4, 0xffff0000, v4
	v_or_b32_sdwa v31, v5, v30 dst_sel:DWORD dst_unused:UNUSED_PAD src0_sel:DWORD src1_sel:WORD_1
	v_or_b32_sdwa v30, v4, v32 dst_sel:DWORD dst_unused:UNUSED_PAD src0_sel:DWORD src1_sel:WORD_1
	v_mov_b32_e32 v5, v44
	v_cndmask_b32_e64 v32, v24, -v24, s[6:7]
	v_cndmask_b32_e64 v33, v26, -v26, s[6:7]
	v_mov_b32_e32 v44, v49
	v_mov_b32_e32 v4, v48
	v_pk_mul_f32 v[32:33], v[32:33], v[44:45]
	v_cndmask_b32_e64 v24, v25, -v25, s[6:7]
	v_pk_fma_f32 v[4:5], v[28:29], v[4:5], v[32:33]
	v_mov_b32_e32 v29, v46
	v_cndmask_b32_e64 v25, v27, -v27, s[6:7]
	v_mov_b32_e32 v46, v51
	v_mov_b32_e32 v28, v50
	v_pk_mul_f32 v[24:25], v[24:25], v[46:47]
	v_pk_mul_f32 v[4:5], s[12:13], v[4:5]
	v_pk_fma_f32 v[2:3], v[2:3], v[28:29], v[24:25]
	v_and_b32_sdwa v24, v5, v204 dst_sel:DWORD dst_unused:UNUSED_PAD src0_sel:WORD_1 src1_sel:DWORD
	v_pk_mul_f32 v[2:3], s[12:13], v[2:3]
	v_and_b32_sdwa v25, v4, v204 dst_sel:DWORD dst_unused:UNUSED_PAD src0_sel:WORD_1 src1_sel:DWORD
	v_add3_u32 v4, v4, v25, s20
	v_add3_u32 v5, v5, v24, s20
	v_and_b32_sdwa v24, v3, v204 dst_sel:DWORD dst_unused:UNUSED_PAD src0_sel:WORD_1 src1_sel:DWORD
	v_and_b32_sdwa v25, v2, v204 dst_sel:DWORD dst_unused:UNUSED_PAD src0_sel:WORD_1 src1_sel:DWORD
	v_add3_u32 v3, v3, v24, s20
	v_add3_u32 v2, v2, v25, s20
	v_and_b32_e32 v3, 0xffff0000, v3
	v_and_b32_e32 v2, 0xffff0000, v2
	v_or_b32_sdwa v33, v3, v5 dst_sel:DWORD dst_unused:UNUSED_PAD src0_sel:DWORD src1_sel:WORD_1
	v_or_b32_sdwa v32, v2, v4 dst_sel:DWORD dst_unused:UNUSED_PAD src0_sel:DWORD src1_sel:WORD_1
	global_store_dwordx4 v[56:57], v[30:33], off
	v_lshl_add_u64 v[2:3], s[82:83], 0, v[8:9]
	v_sub_u32_e32 v249, v2, v250
	ds_read_b32 v2, v249
	s_waitcnt lgkmcnt(0)
	v_fmamk_f32 v2, v2, 0x3a800000, v188
	v_cmp_gt_f32_e32 vcc, s11, v2
	v_mul_f32_e32 v3, 0x4b800000, v2
	s_nop 0
	v_cndmask_b32_e32 v2, v2, v3, vcc
	v_rsq_f32_e32 v2, v2
	s_nop 0
	v_mul_f32_e32 v3, 0x45800000, v2
	v_cndmask_b32_e32 v2, v2, v3, vcc
	v_add_u32_e32 v3, 0x2040, v42
	ds_read2_b32 v[4:5], v3 offset1:1
	s_and_b64 vcc, exec, s[4:5]
	s_waitcnt lgkmcnt(0)
	v_pk_mul_f32 v[24:25], v[4:5], v[2:3] op_sel_hi:[1,0]
	v_add_u32_e32 v3, 0x2040, v41
	ds_read2_b32 v[4:5], v3 offset1:1
	s_waitcnt lgkmcnt(0)
	v_pk_mul_f32 v[30:31], v[4:5], v[2:3] op_sel_hi:[1,0]
	v_add_u32_e32 v3, 0x2048, v42
	ds_read2_b32 v[4:5], v3 offset1:1
	s_waitcnt lgkmcnt(0)
	v_pk_mul_f32 v[36:37], v[4:5], v[2:3] op_sel_hi:[1,0]
	v_add_u32_e32 v3, 0x2048, v41
	ds_read2_b32 v[4:5], v3 offset1:1
	s_waitcnt lgkmcnt(0)
	v_pk_mul_f32 v[34:35], v[4:5], v[2:3] op_sel_hi:[1,0]
	v_add_u32_e32 v3, 0x2050, v42
	ds_read2_b32 v[4:5], v3 offset1:1
	s_waitcnt lgkmcnt(0)
	v_pk_mul_f32 v[26:27], v[2:3], v[4:5] op_sel_hi:[0,1]
	v_add_u32_e32 v3, 0x2050, v41
	ds_read2_b32 v[4:5], v3 offset1:1
	s_waitcnt lgkmcnt(0)
	v_pk_mul_f32 v[28:29], v[2:3], v[4:5] op_sel_hi:[0,1]
	v_add_u32_e32 v3, 0x2058, v42
	ds_read2_b32 v[4:5], v3 offset1:1
	s_waitcnt lgkmcnt(0)
	v_pk_mul_f32 v[38:39], v[2:3], v[4:5] op_sel_hi:[0,1]
	v_add_u32_e32 v3, 0x2058, v41
	ds_read2_b32 v[4:5], v3 offset1:1
	s_waitcnt lgkmcnt(0)
	v_pk_mul_f32 v[32:33], v[2:3], v[4:5] op_sel_hi:[0,1]
	s_cbranch_vccnz .LBB0_143
	v_pk_mul_f32 v[2:3], v[24:25], v[24:25]
	v_pk_mul_f32 v[4:5], v[36:37], v[36:37]
	v_add_f32_e32 v2, v2, v3
	v_add_f32_e32 v2, v4, v2
	v_pk_mul_f32 v[40:41], v[26:27], v[26:27]
	v_add_f32_e32 v2, v5, v2
	v_and_b32_e32 v4, 64, v43
	v_add_f32_e32 v2, v40, v2
	v_xor_b32_e32 v3, 1, v43
	v_add_u32_e32 v4, 64, v4
	v_pk_mul_f32 v[44:45], v[38:39], v[38:39]
	v_add_f32_e32 v2, v41, v2
	v_cmp_lt_i32_e32 vcc, v3, v4
	v_add_f32_e32 v2, v2, v44
	v_add_f32_e32 v2, v2, v45
	v_cndmask_b32_e32 v3, v43, v3, vcc
	v_lshlrev_b32_e32 v3, 2, v3
	ds_bpermute_b32 v3, v3, v2
	s_waitcnt lgkmcnt(0)
	v_add_f32_e32 v2, v2, v3
	v_xor_b32_e32 v3, 2, v43
	v_cmp_lt_i32_e32 vcc, v3, v4
	s_nop 1
	v_cndmask_b32_e32 v3, v43, v3, vcc
	v_lshlrev_b32_e32 v3, 2, v3
	ds_bpermute_b32 v3, v3, v2
	s_waitcnt lgkmcnt(0)
	v_add_f32_e32 v2, v2, v3
	v_xor_b32_e32 v3, 4, v43
	v_cmp_lt_i32_e32 vcc, v3, v4
	s_nop 1
	v_cndmask_b32_e32 v3, v43, v3, vcc
	v_lshlrev_b32_e32 v3, 2, v3
	ds_bpermute_b32 v3, v3, v2
	s_waitcnt lgkmcnt(0)
	v_add_f32_e32 v2, v2, v3
	v_fmamk_f32 v2, v2, 0x3c800000, v188
	v_cmp_gt_f32_e32 vcc, s11, v2
	v_mul_f32_e32 v3, 0x4b800000, v2
	s_nop 0
	v_cndmask_b32_e32 v2, v2, v3, vcc
	v_rsq_f32_e32 v2, v2
	s_nop 0
	v_mul_f32_e32 v3, 0x45800000, v2
	v_cndmask_b32_e32 v40, v2, v3, vcc
	global_load_dwordx4 v[2:5], v[14:15], off offset:16
	global_load_dwordx4 v[42:45], v[14:15], off
	global_load_dwordx4 v[46:49], v[16:17], off offset:16
	global_load_dwordx4 v[50:53], v[16:17], off
	s_waitcnt vmcnt(3)
	v_pk_mul_f32 v[2:3], v[40:41], v[2:3] op_sel_hi:[0,1]
	s_waitcnt vmcnt(2)
	v_pk_mul_f32 v[42:43], v[42:43], v[40:41] op_sel_hi:[1,0]
	v_pk_mul_f32 v[26:27], v[26:27], v[2:3]
	v_pk_mul_f32 v[24:25], v[24:25], v[42:43]
	s_waitcnt vmcnt(0)
	v_pk_mul_f32 v[42:43], v[50:51], v[40:41] op_sel_hi:[1,0]
	v_pk_mul_f32 v[2:3], v[40:41], v[46:47] op_sel_hi:[0,1]
	v_pk_mul_f32 v[30:31], v[30:31], v[42:43]
	v_pk_mul_f32 v[42:43], v[44:45], v[40:41] op_sel_hi:[1,0]
	v_pk_mul_f32 v[28:29], v[28:29], v[2:3]
	v_pk_mul_f32 v[2:3], v[40:41], v[4:5] op_sel_hi:[0,1]
	v_pk_mul_f32 v[36:37], v[36:37], v[42:43]
	v_pk_mul_f32 v[42:43], v[52:53], v[40:41] op_sel_hi:[1,0]
	v_pk_mul_f32 v[38:39], v[38:39], v[2:3]
	v_pk_mul_f32 v[2:3], v[40:41], v[48:49] op_sel_hi:[0,1]
	v_pk_mul_f32 v[34:35], v[34:35], v[42:43]
	v_pk_mul_f32 v[32:33], v[32:33], v[2:3]
	s_branch .LBB0_143
